# attention L0 item epilogue rewritten: gate loads, next-Q loads and output stores row-coalesced through a per-wave LDS tile
# baseline (speedup 1.0000x reference)
; #define LAS __attribute__((address_space(3)))
; __device__ __forceinline__ void attn_phase(const Params& p, LAS unsigned char* lds, int li, int tid, int G, bf16_t* __restrict__ dst, const bf16_t* __restrict__ ZGA) {
;     ...
;     auto dma_stage = [&](int item, int kb, int buf) {
;         int l = tid & 63; asm volatile("" : "+v"(l));
;         const int tb = item >> 2, hk = item & 3, tk = tb * 128 + (kb - 1) * 128;
;         LAS unsigned char* kl = lds + buf * 65536; LAS unsigned char* vl = kl + 32768;
; #pragma unroll
;         for (int i = 0; i < 4; ++i) {
;             const int r = 4 * (4 * w + i) + (l >> 4), c = (l & 15) ^ (r & 15);
;             __builtin_amdgcn_global_load_lds((const unsigned*)(ZK + (size_t)(tk + r) * 512 + hk * 128 + c * 8), (LAS unsigned*)(kl + (4 * w + i) * 1024), 16, 0, 0);
;             __builtin_amdgcn_global_load_lds((const unsigned*)(ZVT + (size_t)(hk * 128 + r) * T + tk + c * 8), (LAS unsigned*)(vl + (4 * w + i) * 1024), 16, 0, 0);
;         }
;     };
;     int buf = 0, curhk = -1;
;     int ibase, istep, icnt;
;     if (G & 7) { ibase = blockIdx.x; istep = G; icnt = ibase < 1024 ? (1024 - ibase + G - 1) / G : 0; }
;     else { const int nper = G >> 3, j0 = blockIdx.x >> 3; ibase = (blockIdx.x & 7) * 128 + j0; istep = nper; icnt = j0 < 128 ? (128 - j0 + nper - 1) / nper : 0; }
;     u32x4 qraw[3][4];
;     auto load_q = [&](int item, int lq_, int g_) {
;         const int tb = item >> 2, hk = item & 3;
; #pragma unroll
;         for (int mb = 0; mb < 3; ++mb) {
;             const int hh = mb, r = 16 * w + lq_;
;             const bf16_t* qp = Z0 + (size_t)(tb * 128 + r) * 2048 + (3 * hk + hh) * 128 + 8 * g_;
; #pragma unroll
;             for (int ks = 0; ks < 4; ++ks) qraw[mb][ks] = *(const u32x4*)(qp + 32 * ks);
;         }
;     };
;     if (icnt > 0) { dma_stage(ibase, 1, 0); load_q(ibase, tid & 15, (tid & 63) >> 4); }
.LBB0_302:
	s_ashr_i32 s1, s0, 6
	v_writelane_b32 v255, s74, 7
	s_waitcnt lgkmcnt(0)
	s_add_u32 s20, s6, 0xae00000
	s_addc_u32 s21, s7, 0
	v_writelane_b32 v255, s75, 8
	v_writelane_b32 v255, s84, 9
	s_add_u32 s22, s6, 0x12e00000
	s_load_dwordx4 s[8:11], s[4:5], 0x30
	v_writelane_b32 v255, s85, 10
	s_addc_u32 s23, s7, 0
	v_writelane_b32 v255, s86, 11
	s_add_u32 s24, s6, 0x14e00000
	v_writelane_b32 v255, s87, 12
	s_addc_u32 s25, s7, 0
	v_writelane_b32 v255, s78, 13
	s_cmp_gt_i32 s14, 0
	s_mov_b32 s27, 0
	v_writelane_b32 v255, s79, 14
	s_cselect_b64 s[4:5], -1, 0
	s_cmp_lt_i32 s14, 1
	v_and_b32_e32 v200, 63, v0
	v_writelane_b32 v255, s73, 15
	s_cbranch_scc1 .LBB0_304
	v_mov_b32_e32 v1, v200
	s_lshl_b32 s17, s15, 5
	s_waitcnt vmcnt(3)
	v_ashrrev_i32_e32 v6, 4, v1
	s_lshl_b32 s28, s1, 4
	s_and_b32 s42, s17, 0xffffff80
	v_add_u32_e32 v7, s28, v6
	v_add_u32_e32 v2, s42, v7
	s_lshl_b32 s17, s15, 7
	v_ashrrev_i32_e32 v3, 31, v2
	s_and_b32 s17, s17, 0x180
	v_xor_b32_e32 v4, v6, v1
	v_lshlrev_b64 v[2:3], 10, v[2:3]
	s_lshl_b32 s18, s1, 12
	v_lshl_add_u64 v[2:3], s[22:23], 0, v[2:3]
	s_lshl_b32 s26, s17, 1
	v_lshlrev_b32_e32 v4, 4, v4
	v_lshl_add_u64 v[2:3], v[2:3], 0, s[26:27]
	v_and_b32_e32 v4, 0xf0, v4
	v_mov_b32_e32 v5, 0
	s_add_i32 s29, s18, 0
	v_lshl_add_u64 v[2:3], v[2:3], 0, v[4:5]
	s_mov_b32 m0, s29
	s_ashr_i32 s43, s42, 31
	global_load_lds_dwordx4 v[2:3], off
	v_add_u32_e32 v2, s17, v7
	v_ashrrev_i32_e32 v3, 31, v2
	v_lshlrev_b64 v[2:3], 16, v[2:3]
	v_lshl_add_u64 v[2:3], s[24:25], 0, v[2:3]
	s_lshl_b64 s[18:19], s[42:43], 1
	s_lshl_b32 s34, s1, 2
	v_lshl_add_u64 v[2:3], v[2:3], 0, s[18:19]
	s_or_b32 s35, s34, 1
	v_lshl_add_u64 v[2:3], v[2:3], 0, v[4:5]
	s_add_i32 m0, s29, 0x8000
	v_lshl_add_u32 v7, s35, 2, v6
	global_load_lds_dwordx4 v[2:3], off
	v_add_u32_e32 v2, s42, v7
	v_ashrrev_i32_e32 v3, 31, v2
	v_xor_b32_e32 v4, v7, v1
	v_lshlrev_b64 v[2:3], 10, v[2:3]
	v_lshl_add_u64 v[2:3], s[22:23], 0, v[2:3]
	v_lshlrev_b32_e32 v4, 4, v4
	v_lshl_add_u64 v[2:3], v[2:3], 0, s[26:27]
	v_and_b32_e32 v4, 0xf0, v4
	s_lshl_b32 s35, s35, 10
	v_lshl_add_u64 v[2:3], v[2:3], 0, v[4:5]
	s_add_i32 m0, s35, 0
	s_or_b32 s35, s34, 2
	global_load_lds_dwordx4 v[2:3], off
	v_add_u32_e32 v2, s17, v7
	v_ashrrev_i32_e32 v3, 31, v2
	v_lshlrev_b64 v[2:3], 16, v[2:3]
	v_lshl_add_u64 v[2:3], s[24:25], 0, v[2:3]
	v_lshl_add_u64 v[2:3], v[2:3], 0, s[18:19]
	v_lshl_add_u64 v[2:3], v[2:3], 0, v[4:5]
	s_add_i32 m0, s29, 0x8400
	v_lshl_add_u32 v7, s35, 2, v6
	global_load_lds_dwordx4 v[2:3], off
	v_add_u32_e32 v2, s42, v7
	v_ashrrev_i32_e32 v3, 31, v2
	v_xor_b32_e32 v4, v7, v1
	v_lshlrev_b64 v[2:3], 10, v[2:3]
	v_lshl_add_u64 v[2:3], s[22:23], 0, v[2:3]
	v_lshlrev_b32_e32 v4, 4, v4
	v_lshl_add_u64 v[2:3], v[2:3], 0, s[26:27]
	v_and_b32_e32 v4, 0xf0, v4
	s_lshl_b32 s35, s35, 10
	v_lshl_add_u64 v[2:3], v[2:3], 0, v[4:5]
	s_add_i32 m0, s35, 0
	s_or_b32 s34, s34, 3
	global_load_lds_dwordx4 v[2:3], off
	v_add_u32_e32 v2, s17, v7
	v_ashrrev_i32_e32 v3, 31, v2
	v_lshlrev_b64 v[2:3], 16, v[2:3]
	v_lshl_add_u64 v[2:3], s[24:25], 0, v[2:3]
	v_lshl_add_u64 v[2:3], v[2:3], 0, s[18:19]
	v_lshl_add_u64 v[2:3], v[2:3], 0, v[4:5]
	s_add_i32 m0, s29, 0x8800
	v_lshl_add_u32 v6, s34, 2, v6
	global_load_lds_dwordx4 v[2:3], off
	v_add_u32_e32 v2, s42, v6
	v_ashrrev_i32_e32 v3, 31, v2
	v_xor_b32_e32 v1, v6, v1
	v_lshlrev_b64 v[2:3], 10, v[2:3]
	v_lshl_add_u64 v[2:3], s[22:23], 0, v[2:3]
	v_lshlrev_b32_e32 v1, 4, v1
	v_lshl_add_u64 v[2:3], v[2:3], 0, s[26:27]
	v_and_b32_e32 v4, 0xf0, v1
	s_lshl_b32 s26, s34, 10
	v_lshl_add_u64 v[2:3], v[2:3], 0, v[4:5]
	s_add_i32 m0, s26, 0
	v_bfe_u32 v1, v0, 3, 3
	v_or_b32_e32 v1, s28, v1
	global_load_lds_dwordx4 v[2:3], off
	v_add_u32_e32 v2, s17, v6
	v_ashrrev_i32_e32 v3, 31, v2
	v_lshlrev_b64 v[2:3], 16, v[2:3]
	v_lshl_add_u64 v[2:3], s[24:25], 0, v[2:3]
	v_lshl_add_u64 v[2:3], v[2:3], 0, s[18:19]
	v_lshl_add_u64 v[2:3], v[2:3], 0, v[4:5]
	s_add_i32 m0, s29, 0x8c00
	s_and_b32 s17, s15, 3
	global_load_lds_dwordx4 v[2:3], off
	v_add_u32_e32 v2, s42, v1
	v_ashrrev_i32_e32 v3, 31, v2
	v_lshlrev_b64 v[2:3], 12, v[2:3]
	v_lshl_add_u64 v[2:3], s[20:21], 0, v[2:3]
	s_mul_i32 s26, s17, 0x300
	v_lshl_add_u64 v[2:3], v[2:3], 0, s[26:27]
	v_and_b32_e32 v4, 7, v0
	v_lshlrev_b32_e32 v4, 4, v4
	v_lshl_add_u64 v[0:1], v[2:3], 0, v[4:5]
	s_mov_b32 s26, 0x8000
	v_lshl_add_u64 v[2:3], v[0:1], 0, s[26:27]
	global_load_dwordx4 v[136:139], v[0:1], off
	global_load_dwordx4 v[106:109], v[2:3], off
	global_load_dwordx4 v[102:105], v[0:1], off offset:128
	global_load_dwordx4 v[98:101], v[2:3], off offset:128
	global_load_dwordx4 v[124:127], v[0:1], off offset:256
	global_load_dwordx4 v[120:123], v[2:3], off offset:256
	global_load_dwordx4 v[116:119], v[0:1], off offset:384
	global_load_dwordx4 v[112:115], v[2:3], off offset:384
	global_load_dwordx4 v[132:135], v[0:1], off offset:512
	global_load_dwordx4 v[128:131], v[2:3], off offset:512
	global_load_dwordx4 v[144:147], v[0:1], off offset:640
	global_load_dwordx4 v[140:143], v[2:3], off offset:640
	s_branch .LBB0_305

; __device__ __forceinline__ unsigned cvt_pk_bf16(float lo, float hi) { unsigned r; asm("v_cvt_pk_bf16_f32 %0, %1, %2" : "=v"(r) : "v"(lo), "v"(hi)); return r; }
; __device__ __forceinline__ float silu_f(float x) { return x * __builtin_amdgcn_rcpf(1.f + __builtin_amdgcn_exp2f(-LOG2E * x)); }
; __device__ __forceinline__ void attn_phase(const Params& p, LAS unsigned char* lds, int li, int tid, int G, bf16_t* __restrict__ dst, const bf16_t* __restrict__ ZGA) {
;     ...
;         u32x2 gv[3][8];
; #pragma unroll
;         for (int mb = 0; mb < 3; ++mb) {
;             const int hh = mb, r = 16 * w + lq;
;             const bf16_t* gp = ZGA + (size_t)(t0 + r) * 1536 + (3 * hk + hh) * 128 + 4 * g;
; #pragma unroll
;             for (int db = 0; db < 8; ++db) gv[mb][db] = *(const u32x2*)(gp + 16 * db);
;         }
;         load_q(nitem >= 0 ? nitem : item, lq, g);
; #pragma unroll
;         for (int mb = 0; mb < 3; ++mb) {
;             const int hh = mb, r = 16 * w + lq;
;             const size_t tok = (size_t)(t0 + r); const int hcol = (3 * hk + hh) * 128 + 4 * g;
;             float lt = lrun[mb]; lt += __shfl_xor(lt, 16); lt += __shfl_xor(lt, 32);
;             lt += __builtin_amdgcn_exp2f(BS[hh * 260 + 257]);
;             const float inv = 1.f / lt;
; #pragma unroll
;             for (int db = 0; db < 8; ++db) {
;                 const f32x4 o = oacc[mb][db] * inv;
;                 u32x2 wv; wv.x = cvt_pk_bf16(o[0] * silu_f(bf_lo(gv[mb][db].x)), o[1] * silu_f(bf_hi(gv[mb][db].x))); wv.y = cvt_pk_bf16(o[2] * silu_f(bf_lo(gv[mb][db].y)), o[3] * silu_f(bf_hi(gv[mb][db].y)));
;                 *(u32x2*)(dst + tok * 2048 + hcol + 16 * db) = wv;
.LBB0_307:
	s_lshl_b32 s0, s38, 7
	s_add_i32 s0, s0, s35
	s_mulk_i32 s46, 0x180
	s_lshl_b32 s1, s46, 1
	v_mbcnt_lo_u32_b32 v197, -1, 0
	v_mbcnt_hi_u32_b32 v197, -1, v197
	v_lshrrev_b32_e32 v198, 3, v197
	v_and_b32_e32 v199, 7, v197
	s_lshl_b32 s4, s35, 7
	s_add_i32 s4, s4, 0x21400
	v_xor_b32_e32 v196, v198, v199
	v_lshlrev_b32_e32 v196, 4, v196
	v_lshl_add_u32 v196, v198, 7, v196
	v_add_u32_e32 v196, s4, v196
	v_add_u32_e32 v210, s0, v198
	v_lshl_add_u32 v212, v199, 4, s1
	v_mov_b32_e32 v213, 0
	s_movk_i32 s0, 0xc00
	v_mad_u64_u32 v[214:215], vcc, v210, s0, v[212:213]
	s_movk_i32 s0, 0x1000
	v_mad_u64_u32 v[220:221], vcc, v210, s0, v[212:213]
	v_lshl_add_u64 v[214:215], v[214:215], 0, s[26:27]
	v_lshl_add_u64 v[220:221], v[220:221], 0, s[42:43]
	s_movk_i32 s18, 0x6000
	s_mov_b32 s19, 0
	v_lshl_add_u64 v[222:223], v[214:215], 0, s[18:19]
	global_load_dwordx4 v[148:151], v[214:215], off
	global_load_dwordx4 v[152:155], v[222:223], off
	global_load_dwordx4 v[156:159], v[214:215], off offset:128
	global_load_dwordx4 v[160:163], v[222:223], off offset:128
	global_load_dwordx4 v[164:167], v[214:215], off offset:256
	global_load_dwordx4 v[168:171], v[222:223], off offset:256
	global_load_dwordx4 v[172:175], v[214:215], off offset:384
	global_load_dwordx4 v[176:179], v[222:223], off offset:384
	global_load_dwordx4 v[180:183], v[214:215], off offset:512
	global_load_dwordx4 v[184:187], v[222:223], off offset:512
	global_load_dwordx4 v[188:191], v[214:215], off offset:640
	global_load_dwordx4 v[192:195], v[222:223], off offset:640
	s_mov_b32 s18, 0x8000
	v_lshl_add_u64 v[224:225], v[220:221], 0, s[18:19]
	s_cmp_lt_i32 s97, 0
	s_cselect_b32 s0, s34, s97
	s_and_b32 s1, s0, 3
	s_lshl_b32 s0, s0, 5
	s_and_b32 s0, s0, 0xffffff80
	s_add_i32 s0, s0, s35
	s_mul_i32 s1, s1, 0x300
	v_add_u32_e32 v210, s0, v198
	v_lshl_add_u32 v212, v199, 4, s1
	s_movk_i32 s0, 0x1000
	v_mad_u64_u32 v[216:217], vcc, v210, s0, v[212:213]
	v_lshl_add_u64 v[216:217], v[216:217], 0, s[20:21]
	v_lshl_add_u64 v[218:219], v[216:217], 0, s[18:19]
	global_load_dwordx4 v[136:139], v[216:217], off
	global_load_dwordx4 v[106:109], v[218:219], off
	global_load_dwordx4 v[102:105], v[216:217], off offset:128
	global_load_dwordx4 v[98:101], v[218:219], off offset:128
	global_load_dwordx4 v[124:127], v[216:217], off offset:256
	global_load_dwordx4 v[120:123], v[218:219], off offset:256
	global_load_dwordx4 v[116:119], v[216:217], off offset:384
	global_load_dwordx4 v[112:115], v[218:219], off offset:384
	global_load_dwordx4 v[132:135], v[216:217], off offset:512
	global_load_dwordx4 v[128:131], v[218:219], off offset:512
	global_load_dwordx4 v[144:147], v[216:217], off offset:640
	global_load_dwordx4 v[140:143], v[218:219], off offset:640
	v_and_b32_e32 v238, 15, v197
	v_lshrrev_b32_e32 v239, 4, v197
	v_lshl_add_u32 v240, v238, 7, s4
	v_and_b32_e32 v241, 1, v239
	v_lshl_add_u32 v240, v241, 3, v240
	v_lshrrev_b32_e32 v241, 1, v239
	v_xor_b32_e32 v241, v241, v238
	v_and_b32_e32 v241, 1, v241
	v_lshl_add_u32 v240, v241, 4, v240
	v_bfe_u32 v241, v238, 1, 2
	v_lshl_add_u32 v248, v241, 5, v240
	v_xor_b32_e32 v249, 32, v248
	v_xor_b32_e32 v250, 64, v248
	v_xor_b32_e32 v251, 0x60, v248
	ds_bpermute_b32 v242, v204, v209
	v_mov_b32_e32 v244, s90
	ds_read_b32 v244, v244
	s_waitcnt lgkmcnt(0)
	v_add_f32_e32 v242, v209, v242
	ds_bpermute_b32 v243, v205, v242
	v_exp_f32_e32 v244, v244
	s_waitcnt lgkmcnt(0)
	v_add_f32_e32 v242, v242, v243
	v_add_f32_e32 v242, v242, v244
	v_div_scale_f32 v238, s[18:19], v242, v242, 1.0
	v_rcp_f32_e32 v239, v238
	s_nop 0
	v_fma_f32 v240, -v238, v239, 1.0
	v_fmac_f32_e32 v239, v240, v239
	v_div_scale_f32 v240, vcc, 1.0, v242, 1.0
	v_mul_f32_e32 v241, v240, v239
	v_fma_f32 v245, -v238, v241, v240
	v_fmac_f32_e32 v241, v245, v239
	v_fma_f32 v240, -v238, v241, v240
	v_div_fmas_f32 v240, v240, v239, v241
	v_div_fixup_f32 v226, v240, v242, 1.0
	ds_bpermute_b32 v242, v204, v207
	v_mov_b32_e32 v244, s91
	ds_read_b32 v244, v244
	s_waitcnt lgkmcnt(0)
	v_add_f32_e32 v242, v207, v242
	ds_bpermute_b32 v243, v205, v242
	v_exp_f32_e32 v244, v244
	s_waitcnt lgkmcnt(0)
	v_add_f32_e32 v242, v242, v243
	v_add_f32_e32 v242, v242, v244
	v_div_scale_f32 v238, s[18:19], v242, v242, 1.0
	v_rcp_f32_e32 v239, v238
	s_nop 0
	v_fma_f32 v240, -v238, v239, 1.0
	v_fmac_f32_e32 v239, v240, v239
	v_div_scale_f32 v240, vcc, 1.0, v242, 1.0
	v_mul_f32_e32 v241, v240, v239
	v_fma_f32 v245, -v238, v241, v240
	v_fmac_f32_e32 v241, v245, v239
	v_fma_f32 v240, -v238, v241, v240
	v_div_fmas_f32 v240, v240, v239, v241
	v_div_fixup_f32 v228, v240, v242, 1.0
	ds_bpermute_b32 v242, v204, v206
	v_mov_b32_e32 v244, s92
	ds_read_b32 v244, v244
	s_waitcnt lgkmcnt(0)
	v_add_f32_e32 v242, v206, v242
	ds_bpermute_b32 v243, v205, v242
	v_exp_f32_e32 v244, v244
	s_waitcnt lgkmcnt(0)
	v_add_f32_e32 v242, v242, v243
	v_add_f32_e32 v242, v242, v244
	v_div_scale_f32 v238, s[18:19], v242, v242, 1.0
	v_rcp_f32_e32 v239, v238
	s_nop 0
	v_fma_f32 v240, -v238, v239, 1.0
	v_fmac_f32_e32 v239, v240, v239
	v_div_scale_f32 v240, vcc, 1.0, v242, 1.0
	v_mul_f32_e32 v241, v240, v239
	v_fma_f32 v245, -v238, v241, v240
	v_fmac_f32_e32 v241, v245, v239
	v_fma_f32 v240, -v238, v241, v240
	v_div_fmas_f32 v240, v240, v239, v241
	v_div_fixup_f32 v246, v240, v242, 1.0
	s_waitcnt vmcnt(22)
	ds_write_b128 v196, v[148:151]
	ds_write_b128 v196, v[152:155] offset:1024
	ds_read_b64 v[230:231], v248
	ds_read_b64 v[232:233], v249
	ds_read_b64 v[234:235], v250
	ds_read_b64 v[236:237], v251
	s_waitcnt lgkmcnt(0)
; __device__ __forceinline__ unsigned cvt_pk_bf16(float lo, float hi) { unsigned r; asm("v_cvt_pk_bf16_f32 %0, %1, %2" : "=v"(r) : "v"(lo), "v"(hi)); return r; }
; __device__ __forceinline__ float silu_f(float x) { return x * __builtin_amdgcn_rcpf(1.f + __builtin_amdgcn_exp2f(-LOG2E * x)); }
; __device__ __forceinline__ void attn_phase(const Params& p, LAS unsigned char* lds, int li, int tid, int G, bf16_t* __restrict__ dst, const bf16_t* __restrict__ ZGA) {
;     ...
; #pragma unroll
;         for (int mb = 0; mb < 3; ++mb) {
;             const int hh = mb, r = 16 * w + lq;
;             const size_t tok = (size_t)(t0 + r); const int hcol = (3 * hk + hh) * 128 + 4 * g;
;             float lt = lrun[mb]; lt += __shfl_xor(lt, 16); lt += __shfl_xor(lt, 32);
;             lt += __builtin_amdgcn_exp2f(BS[hh * 260 + 257]);
;             const float inv = 1.f / lt;
; #pragma unroll
;             for (int db = 0; db < 8; ++db) {
;                 const f32x4 o = oacc[mb][db] * inv;
;                 u32x2 wv; wv.x = cvt_pk_bf16(o[0] * silu_f(bf_lo(gv[mb][db].x)), o[1] * silu_f(bf_hi(gv[mb][db].x))); wv.y = cvt_pk_bf16(o[2] * silu_f(bf_lo(gv[mb][db].y)), o[3] * silu_f(bf_hi(gv[mb][db].y)));
;                 *(u32x2*)(dst + tok * 2048 + hcol + 16 * db) = wv;
;             }
;         }
	v_pk_mul_f32 v[94:95], v[94:95], v[226:227] op_sel_hi:[1,0]
	v_pk_mul_f32 v[96:97], v[96:97], v[226:227] op_sel_hi:[1,0]
	v_lshlrev_b32_e32 v238, 16, v230
	v_and_b32_e32 v239, 0xffff0000, v230
	v_lshlrev_b32_e32 v240, 16, v231
	v_and_b32_e32 v241, 0xffff0000, v231
	v_mul_f32_e32 v242, 0xbfb8aa3b, v238
	v_mul_f32_e32 v243, 0xbfb8aa3b, v239
	v_mul_f32_e32 v244, 0xbfb8aa3b, v240
	v_mul_f32_e32 v245, 0xbfb8aa3b, v241
	v_exp_f32_e32 v242, v242
	v_exp_f32_e32 v243, v243
	v_exp_f32_e32 v244, v244
	v_exp_f32_e32 v245, v245
	v_add_f32_e32 v242, 1.0, v242
	v_add_f32_e32 v243, 1.0, v243
	v_add_f32_e32 v244, 1.0, v244
	v_add_f32_e32 v245, 1.0, v245
	v_rcp_f32_e32 v242, v242
	v_rcp_f32_e32 v243, v243
	v_rcp_f32_e32 v244, v244
	v_rcp_f32_e32 v245, v245
	v_mul_f32_e32 v242, v242, v238
	v_mul_f32_e32 v243, v243, v239
	v_mul_f32_e32 v244, v244, v240
	v_mul_f32_e32 v245, v245, v241
	v_mul_f32_e32 v94, v242, v94
	v_mul_f32_e32 v95, v243, v95
	v_mul_f32_e32 v96, v244, v96
	v_mul_f32_e32 v97, v245, v97
	v_cvt_pk_bf16_f32 v230, v94, v95
	v_cvt_pk_bf16_f32 v231, v96, v97
	v_pk_mul_f32 v[90:91], v[90:91], v[226:227] op_sel_hi:[1,0]
	v_pk_mul_f32 v[92:93], v[92:93], v[226:227] op_sel_hi:[1,0]
	v_lshlrev_b32_e32 v238, 16, v232
	v_and_b32_e32 v239, 0xffff0000, v232
	v_lshlrev_b32_e32 v240, 16, v233
	v_and_b32_e32 v241, 0xffff0000, v233
	v_mul_f32_e32 v242, 0xbfb8aa3b, v238
	v_mul_f32_e32 v243, 0xbfb8aa3b, v239
	v_mul_f32_e32 v244, 0xbfb8aa3b, v240
	v_mul_f32_e32 v245, 0xbfb8aa3b, v241
	v_exp_f32_e32 v242, v242
	v_exp_f32_e32 v243, v243
	v_exp_f32_e32 v244, v244
	v_exp_f32_e32 v245, v245
	v_add_f32_e32 v242, 1.0, v242
	v_add_f32_e32 v243, 1.0, v243
	v_add_f32_e32 v244, 1.0, v244
	v_add_f32_e32 v245, 1.0, v245
	v_rcp_f32_e32 v242, v242
	v_rcp_f32_e32 v243, v243
	v_rcp_f32_e32 v244, v244
	v_rcp_f32_e32 v245, v245
	v_mul_f32_e32 v242, v242, v238
	v_mul_f32_e32 v243, v243, v239
	v_mul_f32_e32 v244, v244, v240
	v_mul_f32_e32 v245, v245, v241
	v_mul_f32_e32 v90, v242, v90
	v_mul_f32_e32 v91, v243, v91
	v_mul_f32_e32 v92, v244, v92
	v_mul_f32_e32 v93, v245, v93
	v_cvt_pk_bf16_f32 v232, v90, v91
	v_cvt_pk_bf16_f32 v233, v92, v93
	v_pk_mul_f32 v[86:87], v[86:87], v[226:227] op_sel_hi:[1,0]
	v_pk_mul_f32 v[88:89], v[88:89], v[226:227] op_sel_hi:[1,0]
	v_lshlrev_b32_e32 v238, 16, v234
	v_and_b32_e32 v239, 0xffff0000, v234
	v_lshlrev_b32_e32 v240, 16, v235
	v_and_b32_e32 v241, 0xffff0000, v235
	v_mul_f32_e32 v242, 0xbfb8aa3b, v238
	v_mul_f32_e32 v243, 0xbfb8aa3b, v239
	v_mul_f32_e32 v244, 0xbfb8aa3b, v240
	v_mul_f32_e32 v245, 0xbfb8aa3b, v241
	v_exp_f32_e32 v242, v242
	v_exp_f32_e32 v243, v243
	v_exp_f32_e32 v244, v244
	v_exp_f32_e32 v245, v245
	v_add_f32_e32 v242, 1.0, v242
	v_add_f32_e32 v243, 1.0, v243
	v_add_f32_e32 v244, 1.0, v244
	v_add_f32_e32 v245, 1.0, v245
	v_rcp_f32_e32 v242, v242
	v_rcp_f32_e32 v243, v243
	v_rcp_f32_e32 v244, v244
	v_rcp_f32_e32 v245, v245
	v_mul_f32_e32 v242, v242, v238
	v_mul_f32_e32 v243, v243, v239
	v_mul_f32_e32 v244, v244, v240
	v_mul_f32_e32 v245, v245, v241
	v_mul_f32_e32 v86, v242, v86
	v_mul_f32_e32 v87, v243, v87
	v_mul_f32_e32 v88, v244, v88
	v_mul_f32_e32 v89, v245, v89
	v_cvt_pk_bf16_f32 v234, v86, v87
	v_cvt_pk_bf16_f32 v235, v88, v89
	v_pk_mul_f32 v[82:83], v[82:83], v[226:227] op_sel_hi:[1,0]
	v_pk_mul_f32 v[84:85], v[84:85], v[226:227] op_sel_hi:[1,0]
	v_lshlrev_b32_e32 v238, 16, v236
	v_and_b32_e32 v239, 0xffff0000, v236
	v_lshlrev_b32_e32 v240, 16, v237
	v_and_b32_e32 v241, 0xffff0000, v237
	v_mul_f32_e32 v242, 0xbfb8aa3b, v238
	v_mul_f32_e32 v243, 0xbfb8aa3b, v239
	v_mul_f32_e32 v244, 0xbfb8aa3b, v240
	v_mul_f32_e32 v245, 0xbfb8aa3b, v241
	v_exp_f32_e32 v242, v242
	v_exp_f32_e32 v243, v243
	v_exp_f32_e32 v244, v244
	v_exp_f32_e32 v245, v245
	v_add_f32_e32 v242, 1.0, v242
	v_add_f32_e32 v243, 1.0, v243
	v_add_f32_e32 v244, 1.0, v244
	v_add_f32_e32 v245, 1.0, v245
	v_rcp_f32_e32 v242, v242
	v_rcp_f32_e32 v243, v243
	v_rcp_f32_e32 v244, v244
	v_rcp_f32_e32 v245, v245
	v_mul_f32_e32 v242, v242, v238
	v_mul_f32_e32 v243, v243, v239
	v_mul_f32_e32 v244, v244, v240
	v_mul_f32_e32 v245, v245, v241
	v_mul_f32_e32 v82, v242, v82
	v_mul_f32_e32 v83, v243, v83
	v_mul_f32_e32 v84, v244, v84
	v_mul_f32_e32 v85, v245, v85
	v_cvt_pk_bf16_f32 v236, v82, v83
	v_cvt_pk_bf16_f32 v237, v84, v85
	ds_write_b64 v248, v[230:231]
	ds_write_b64 v249, v[232:233]
	ds_write_b64 v250, v[234:235]
	ds_write_b64 v251, v[236:237]
	ds_read_b128 v[94:97], v196
	ds_read_b128 v[90:93], v196 offset:1024
	s_waitcnt vmcnt(20)
	ds_write_b128 v196, v[156:159]
	ds_write_b128 v196, v[160:163] offset:1024
	ds_read_b64 v[230:231], v248
	ds_read_b64 v[232:233], v249
	ds_read_b64 v[234:235], v250
	ds_read_b64 v[236:237], v251
	s_waitcnt lgkmcnt(4)
	global_store_dwordx4 v[220:221], v[94:97], off
	global_store_dwordx4 v[224:225], v[90:93], off
	s_waitcnt lgkmcnt(0)
; __device__ __forceinline__ unsigned cvt_pk_bf16(float lo, float hi) { unsigned r; asm("v_cvt_pk_bf16_f32 %0, %1, %2" : "=v"(r) : "v"(lo), "v"(hi)); return r; }
; __device__ __forceinline__ float silu_f(float x) { return x * __builtin_amdgcn_rcpf(1.f + __builtin_amdgcn_exp2f(-LOG2E * x)); }
; __device__ __forceinline__ void attn_phase(const Params& p, LAS unsigned char* lds, int li, int tid, int G, bf16_t* __restrict__ dst, const bf16_t* __restrict__ ZGA) {
;     ...
; #pragma unroll
;         for (int mb = 0; mb < 3; ++mb) {
;             const int hh = mb, r = 16 * w + lq;
;             const size_t tok = (size_t)(t0 + r); const int hcol = (3 * hk + hh) * 128 + 4 * g;
;             float lt = lrun[mb]; lt += __shfl_xor(lt, 16); lt += __shfl_xor(lt, 32);
;             lt += __builtin_amdgcn_exp2f(BS[hh * 260 + 257]);
;             const float inv = 1.f / lt;
; #pragma unroll
;             for (int db = 0; db < 8; ++db) {
;                 const f32x4 o = oacc[mb][db] * inv;
;                 u32x2 wv; wv.x = cvt_pk_bf16(o[0] * silu_f(bf_lo(gv[mb][db].x)), o[1] * silu_f(bf_hi(gv[mb][db].x))); wv.y = cvt_pk_bf16(o[2] * silu_f(bf_lo(gv[mb][db].y)), o[3] * silu_f(bf_hi(gv[mb][db].y)));
;                 *(u32x2*)(dst + tok * 2048 + hcol + 16 * db) = wv;
;             }
;         }
	v_pk_mul_f32 v[78:79], v[78:79], v[226:227] op_sel_hi:[1,0]
	v_pk_mul_f32 v[80:81], v[80:81], v[226:227] op_sel_hi:[1,0]
	v_lshlrev_b32_e32 v238, 16, v230
	v_and_b32_e32 v239, 0xffff0000, v230
	v_lshlrev_b32_e32 v240, 16, v231
	v_and_b32_e32 v241, 0xffff0000, v231
	v_mul_f32_e32 v242, 0xbfb8aa3b, v238
	v_mul_f32_e32 v243, 0xbfb8aa3b, v239
	v_mul_f32_e32 v244, 0xbfb8aa3b, v240
	v_mul_f32_e32 v245, 0xbfb8aa3b, v241
	v_exp_f32_e32 v242, v242
	v_exp_f32_e32 v243, v243
	v_exp_f32_e32 v244, v244
	v_exp_f32_e32 v245, v245
	v_add_f32_e32 v242, 1.0, v242
	v_add_f32_e32 v243, 1.0, v243
	v_add_f32_e32 v244, 1.0, v244
	v_add_f32_e32 v245, 1.0, v245
	v_rcp_f32_e32 v242, v242
	v_rcp_f32_e32 v243, v243
	v_rcp_f32_e32 v244, v244
	v_rcp_f32_e32 v245, v245
	v_mul_f32_e32 v242, v242, v238
	v_mul_f32_e32 v243, v243, v239
	v_mul_f32_e32 v244, v244, v240
	v_mul_f32_e32 v245, v245, v241
	v_mul_f32_e32 v78, v242, v78
	v_mul_f32_e32 v79, v243, v79
	v_mul_f32_e32 v80, v244, v80
	v_mul_f32_e32 v81, v245, v81
	v_cvt_pk_bf16_f32 v230, v78, v79
	v_cvt_pk_bf16_f32 v231, v80, v81
	v_pk_mul_f32 v[74:75], v[74:75], v[226:227] op_sel_hi:[1,0]
	v_pk_mul_f32 v[76:77], v[76:77], v[226:227] op_sel_hi:[1,0]
	v_lshlrev_b32_e32 v238, 16, v232
	v_and_b32_e32 v239, 0xffff0000, v232
	v_lshlrev_b32_e32 v240, 16, v233
	v_and_b32_e32 v241, 0xffff0000, v233
	v_mul_f32_e32 v242, 0xbfb8aa3b, v238
	v_mul_f32_e32 v243, 0xbfb8aa3b, v239
	v_mul_f32_e32 v244, 0xbfb8aa3b, v240
	v_mul_f32_e32 v245, 0xbfb8aa3b, v241
	v_exp_f32_e32 v242, v242
	v_exp_f32_e32 v243, v243
	v_exp_f32_e32 v244, v244
	v_exp_f32_e32 v245, v245
	v_add_f32_e32 v242, 1.0, v242
	v_add_f32_e32 v243, 1.0, v243
	v_add_f32_e32 v244, 1.0, v244
	v_add_f32_e32 v245, 1.0, v245
	v_rcp_f32_e32 v242, v242
	v_rcp_f32_e32 v243, v243
	v_rcp_f32_e32 v244, v244
	v_rcp_f32_e32 v245, v245
	v_mul_f32_e32 v242, v242, v238
	v_mul_f32_e32 v243, v243, v239
	v_mul_f32_e32 v244, v244, v240
	v_mul_f32_e32 v245, v245, v241
	v_mul_f32_e32 v74, v242, v74
	v_mul_f32_e32 v75, v243, v75
	v_mul_f32_e32 v76, v244, v76
	v_mul_f32_e32 v77, v245, v77
	v_cvt_pk_bf16_f32 v232, v74, v75
	v_cvt_pk_bf16_f32 v233, v76, v77
	v_pk_mul_f32 v[70:71], v[70:71], v[226:227] op_sel_hi:[1,0]
	v_pk_mul_f32 v[72:73], v[72:73], v[226:227] op_sel_hi:[1,0]
	v_lshlrev_b32_e32 v238, 16, v234
	v_and_b32_e32 v239, 0xffff0000, v234
	v_lshlrev_b32_e32 v240, 16, v235
	v_and_b32_e32 v241, 0xffff0000, v235
	v_mul_f32_e32 v242, 0xbfb8aa3b, v238
	v_mul_f32_e32 v243, 0xbfb8aa3b, v239
	v_mul_f32_e32 v244, 0xbfb8aa3b, v240
	v_mul_f32_e32 v245, 0xbfb8aa3b, v241
	v_exp_f32_e32 v242, v242
	v_exp_f32_e32 v243, v243
	v_exp_f32_e32 v244, v244
	v_exp_f32_e32 v245, v245
	v_add_f32_e32 v242, 1.0, v242
	v_add_f32_e32 v243, 1.0, v243
	v_add_f32_e32 v244, 1.0, v244
	v_add_f32_e32 v245, 1.0, v245
	v_rcp_f32_e32 v242, v242
	v_rcp_f32_e32 v243, v243
	v_rcp_f32_e32 v244, v244
	v_rcp_f32_e32 v245, v245
	v_mul_f32_e32 v242, v242, v238
	v_mul_f32_e32 v243, v243, v239
	v_mul_f32_e32 v244, v244, v240
	v_mul_f32_e32 v245, v245, v241
	v_mul_f32_e32 v70, v242, v70
	v_mul_f32_e32 v71, v243, v71
	v_mul_f32_e32 v72, v244, v72
	v_mul_f32_e32 v73, v245, v73
	v_cvt_pk_bf16_f32 v234, v70, v71
	v_cvt_pk_bf16_f32 v235, v72, v73
	v_pk_mul_f32 v[66:67], v[66:67], v[226:227] op_sel_hi:[1,0]
	v_pk_mul_f32 v[68:69], v[68:69], v[226:227] op_sel_hi:[1,0]
	v_lshlrev_b32_e32 v238, 16, v236
	v_and_b32_e32 v239, 0xffff0000, v236
	v_lshlrev_b32_e32 v240, 16, v237
	v_and_b32_e32 v241, 0xffff0000, v237
	v_mul_f32_e32 v242, 0xbfb8aa3b, v238
	v_mul_f32_e32 v243, 0xbfb8aa3b, v239
	v_mul_f32_e32 v244, 0xbfb8aa3b, v240
	v_mul_f32_e32 v245, 0xbfb8aa3b, v241
	v_exp_f32_e32 v242, v242
	v_exp_f32_e32 v243, v243
	v_exp_f32_e32 v244, v244
	v_exp_f32_e32 v245, v245
	v_add_f32_e32 v242, 1.0, v242
	v_add_f32_e32 v243, 1.0, v243
	v_add_f32_e32 v244, 1.0, v244
	v_add_f32_e32 v245, 1.0, v245
	v_rcp_f32_e32 v242, v242
	v_rcp_f32_e32 v243, v243
	v_rcp_f32_e32 v244, v244
	v_rcp_f32_e32 v245, v245
	v_mul_f32_e32 v242, v242, v238
	v_mul_f32_e32 v243, v243, v239
	v_mul_f32_e32 v244, v244, v240
	v_mul_f32_e32 v245, v245, v241
	v_mul_f32_e32 v66, v242, v66
	v_mul_f32_e32 v67, v243, v67
	v_mul_f32_e32 v68, v244, v68
	v_mul_f32_e32 v69, v245, v69
	v_cvt_pk_bf16_f32 v236, v66, v67
	v_cvt_pk_bf16_f32 v237, v68, v69
	ds_write_b64 v248, v[230:231]
	ds_write_b64 v249, v[232:233]
	ds_write_b64 v250, v[234:235]
	ds_write_b64 v251, v[236:237]
	ds_read_b128 v[78:81], v196
	ds_read_b128 v[74:77], v196 offset:1024
	s_waitcnt vmcnt(20)
	ds_write_b128 v196, v[164:167]
	ds_write_b128 v196, v[168:171] offset:1024
	ds_read_b64 v[230:231], v248
	ds_read_b64 v[232:233], v249
	ds_read_b64 v[234:235], v250
	ds_read_b64 v[236:237], v251
	s_waitcnt lgkmcnt(4)
	global_store_dwordx4 v[220:221], v[78:81], off offset:128
	global_store_dwordx4 v[224:225], v[74:77], off offset:128
	s_waitcnt lgkmcnt(0)
; __device__ __forceinline__ unsigned cvt_pk_bf16(float lo, float hi) { unsigned r; asm("v_cvt_pk_bf16_f32 %0, %1, %2" : "=v"(r) : "v"(lo), "v"(hi)); return r; }
; __device__ __forceinline__ float silu_f(float x) { return x * __builtin_amdgcn_rcpf(1.f + __builtin_amdgcn_exp2f(-LOG2E * x)); }
; __device__ __forceinline__ void attn_phase(const Params& p, LAS unsigned char* lds, int li, int tid, int G, bf16_t* __restrict__ dst, const bf16_t* __restrict__ ZGA) {
;     ...
; #pragma unroll
;         for (int mb = 0; mb < 3; ++mb) {
;             const int hh = mb, r = 16 * w + lq;
;             const size_t tok = (size_t)(t0 + r); const int hcol = (3 * hk + hh) * 128 + 4 * g;
;             float lt = lrun[mb]; lt += __shfl_xor(lt, 16); lt += __shfl_xor(lt, 32);
;             lt += __builtin_amdgcn_exp2f(BS[hh * 260 + 257]);
;             const float inv = 1.f / lt;
; #pragma unroll
;             for (int db = 0; db < 8; ++db) {
;                 const f32x4 o = oacc[mb][db] * inv;
;                 u32x2 wv; wv.x = cvt_pk_bf16(o[0] * silu_f(bf_lo(gv[mb][db].x)), o[1] * silu_f(bf_hi(gv[mb][db].x))); wv.y = cvt_pk_bf16(o[2] * silu_f(bf_lo(gv[mb][db].y)), o[3] * silu_f(bf_hi(gv[mb][db].y)));
;                 *(u32x2*)(dst + tok * 2048 + hcol + 16 * db) = wv;
;             }
;         }
	v_pk_mul_f32 v[62:63], v[62:63], v[228:229] op_sel_hi:[1,0]
	v_pk_mul_f32 v[64:65], v[64:65], v[228:229] op_sel_hi:[1,0]
	v_lshlrev_b32_e32 v238, 16, v230
	v_and_b32_e32 v239, 0xffff0000, v230
	v_lshlrev_b32_e32 v240, 16, v231
	v_and_b32_e32 v241, 0xffff0000, v231
	v_mul_f32_e32 v242, 0xbfb8aa3b, v238
	v_mul_f32_e32 v243, 0xbfb8aa3b, v239
	v_mul_f32_e32 v244, 0xbfb8aa3b, v240
	v_mul_f32_e32 v245, 0xbfb8aa3b, v241
	v_exp_f32_e32 v242, v242
	v_exp_f32_e32 v243, v243
	v_exp_f32_e32 v244, v244
	v_exp_f32_e32 v245, v245
	v_add_f32_e32 v242, 1.0, v242
	v_add_f32_e32 v243, 1.0, v243
	v_add_f32_e32 v244, 1.0, v244
	v_add_f32_e32 v245, 1.0, v245
	v_rcp_f32_e32 v242, v242
	v_rcp_f32_e32 v243, v243
	v_rcp_f32_e32 v244, v244
	v_rcp_f32_e32 v245, v245
	v_mul_f32_e32 v242, v242, v238
	v_mul_f32_e32 v243, v243, v239
	v_mul_f32_e32 v244, v244, v240
	v_mul_f32_e32 v245, v245, v241
	v_mul_f32_e32 v62, v242, v62
	v_mul_f32_e32 v63, v243, v63
	v_mul_f32_e32 v64, v244, v64
	v_mul_f32_e32 v65, v245, v65
	v_cvt_pk_bf16_f32 v230, v62, v63
	v_cvt_pk_bf16_f32 v231, v64, v65
	v_pk_mul_f32 v[58:59], v[58:59], v[228:229] op_sel_hi:[1,0]
	v_pk_mul_f32 v[60:61], v[60:61], v[228:229] op_sel_hi:[1,0]
	v_lshlrev_b32_e32 v238, 16, v232
	v_and_b32_e32 v239, 0xffff0000, v232
	v_lshlrev_b32_e32 v240, 16, v233
	v_and_b32_e32 v241, 0xffff0000, v233
	v_mul_f32_e32 v242, 0xbfb8aa3b, v238
	v_mul_f32_e32 v243, 0xbfb8aa3b, v239
	v_mul_f32_e32 v244, 0xbfb8aa3b, v240
	v_mul_f32_e32 v245, 0xbfb8aa3b, v241
	v_exp_f32_e32 v242, v242
	v_exp_f32_e32 v243, v243
	v_exp_f32_e32 v244, v244
	v_exp_f32_e32 v245, v245
	v_add_f32_e32 v242, 1.0, v242
	v_add_f32_e32 v243, 1.0, v243
	v_add_f32_e32 v244, 1.0, v244
	v_add_f32_e32 v245, 1.0, v245
	v_rcp_f32_e32 v242, v242
	v_rcp_f32_e32 v243, v243
	v_rcp_f32_e32 v244, v244
	v_rcp_f32_e32 v245, v245
	v_mul_f32_e32 v242, v242, v238
	v_mul_f32_e32 v243, v243, v239
	v_mul_f32_e32 v244, v244, v240
	v_mul_f32_e32 v245, v245, v241
	v_mul_f32_e32 v58, v242, v58
	v_mul_f32_e32 v59, v243, v59
	v_mul_f32_e32 v60, v244, v60
	v_mul_f32_e32 v61, v245, v61
	v_cvt_pk_bf16_f32 v232, v58, v59
	v_cvt_pk_bf16_f32 v233, v60, v61
	v_pk_mul_f32 v[54:55], v[54:55], v[228:229] op_sel_hi:[1,0]
	v_pk_mul_f32 v[56:57], v[56:57], v[228:229] op_sel_hi:[1,0]
	v_lshlrev_b32_e32 v238, 16, v234
	v_and_b32_e32 v239, 0xffff0000, v234
	v_lshlrev_b32_e32 v240, 16, v235
	v_and_b32_e32 v241, 0xffff0000, v235
	v_mul_f32_e32 v242, 0xbfb8aa3b, v238
	v_mul_f32_e32 v243, 0xbfb8aa3b, v239
	v_mul_f32_e32 v244, 0xbfb8aa3b, v240
	v_mul_f32_e32 v245, 0xbfb8aa3b, v241
	v_exp_f32_e32 v242, v242
	v_exp_f32_e32 v243, v243
	v_exp_f32_e32 v244, v244
	v_exp_f32_e32 v245, v245
	v_add_f32_e32 v242, 1.0, v242
	v_add_f32_e32 v243, 1.0, v243
	v_add_f32_e32 v244, 1.0, v244
	v_add_f32_e32 v245, 1.0, v245
	v_rcp_f32_e32 v242, v242
	v_rcp_f32_e32 v243, v243
	v_rcp_f32_e32 v244, v244
	v_rcp_f32_e32 v245, v245
	v_mul_f32_e32 v242, v242, v238
	v_mul_f32_e32 v243, v243, v239
	v_mul_f32_e32 v244, v244, v240
	v_mul_f32_e32 v245, v245, v241
	v_mul_f32_e32 v54, v242, v54
	v_mul_f32_e32 v55, v243, v55
	v_mul_f32_e32 v56, v244, v56
	v_mul_f32_e32 v57, v245, v57
	v_cvt_pk_bf16_f32 v234, v54, v55
	v_cvt_pk_bf16_f32 v235, v56, v57
	v_pk_mul_f32 v[50:51], v[50:51], v[228:229] op_sel_hi:[1,0]
	v_pk_mul_f32 v[52:53], v[52:53], v[228:229] op_sel_hi:[1,0]
	v_lshlrev_b32_e32 v238, 16, v236
	v_and_b32_e32 v239, 0xffff0000, v236
	v_lshlrev_b32_e32 v240, 16, v237
	v_and_b32_e32 v241, 0xffff0000, v237
	v_mul_f32_e32 v242, 0xbfb8aa3b, v238
	v_mul_f32_e32 v243, 0xbfb8aa3b, v239
	v_mul_f32_e32 v244, 0xbfb8aa3b, v240
	v_mul_f32_e32 v245, 0xbfb8aa3b, v241
	v_exp_f32_e32 v242, v242
	v_exp_f32_e32 v243, v243
	v_exp_f32_e32 v244, v244
	v_exp_f32_e32 v245, v245
	v_add_f32_e32 v242, 1.0, v242
	v_add_f32_e32 v243, 1.0, v243
	v_add_f32_e32 v244, 1.0, v244
	v_add_f32_e32 v245, 1.0, v245
	v_rcp_f32_e32 v242, v242
	v_rcp_f32_e32 v243, v243
	v_rcp_f32_e32 v244, v244
	v_rcp_f32_e32 v245, v245
	v_mul_f32_e32 v242, v242, v238
	v_mul_f32_e32 v243, v243, v239
	v_mul_f32_e32 v244, v244, v240
	v_mul_f32_e32 v245, v245, v241
	v_mul_f32_e32 v50, v242, v50
	v_mul_f32_e32 v51, v243, v51
	v_mul_f32_e32 v52, v244, v52
	v_mul_f32_e32 v53, v245, v53
	v_cvt_pk_bf16_f32 v236, v50, v51
	v_cvt_pk_bf16_f32 v237, v52, v53
	ds_write_b64 v248, v[230:231]
	ds_write_b64 v249, v[232:233]
	ds_write_b64 v250, v[234:235]
	ds_write_b64 v251, v[236:237]
	ds_read_b128 v[62:65], v196
	ds_read_b128 v[58:61], v196 offset:1024
	s_waitcnt vmcnt(20)
	ds_write_b128 v196, v[172:175]
	ds_write_b128 v196, v[176:179] offset:1024
	ds_read_b64 v[230:231], v248
	ds_read_b64 v[232:233], v249
	ds_read_b64 v[234:235], v250
	ds_read_b64 v[236:237], v251
	s_waitcnt lgkmcnt(4)
	global_store_dwordx4 v[220:221], v[62:65], off offset:256
	global_store_dwordx4 v[224:225], v[58:61], off offset:256
	s_waitcnt lgkmcnt(0)
; __device__ __forceinline__ unsigned cvt_pk_bf16(float lo, float hi) { unsigned r; asm("v_cvt_pk_bf16_f32 %0, %1, %2" : "=v"(r) : "v"(lo), "v"(hi)); return r; }
; __device__ __forceinline__ float silu_f(float x) { return x * __builtin_amdgcn_rcpf(1.f + __builtin_amdgcn_exp2f(-LOG2E * x)); }
; __device__ __forceinline__ void attn_phase(const Params& p, LAS unsigned char* lds, int li, int tid, int G, bf16_t* __restrict__ dst, const bf16_t* __restrict__ ZGA) {
;     ...
; #pragma unroll
;         for (int mb = 0; mb < 3; ++mb) {
;             const int hh = mb, r = 16 * w + lq;
;             const size_t tok = (size_t)(t0 + r); const int hcol = (3 * hk + hh) * 128 + 4 * g;
;             float lt = lrun[mb]; lt += __shfl_xor(lt, 16); lt += __shfl_xor(lt, 32);
;             lt += __builtin_amdgcn_exp2f(BS[hh * 260 + 257]);
;             const float inv = 1.f / lt;
; #pragma unroll
;             for (int db = 0; db < 8; ++db) {
;                 const f32x4 o = oacc[mb][db] * inv;
;                 u32x2 wv; wv.x = cvt_pk_bf16(o[0] * silu_f(bf_lo(gv[mb][db].x)), o[1] * silu_f(bf_hi(gv[mb][db].x))); wv.y = cvt_pk_bf16(o[2] * silu_f(bf_lo(gv[mb][db].y)), o[3] * silu_f(bf_hi(gv[mb][db].y)));
;                 *(u32x2*)(dst + tok * 2048 + hcol + 16 * db) = wv;
;             }
;         }
	v_pk_mul_f32 v[46:47], v[46:47], v[228:229] op_sel_hi:[1,0]
	v_pk_mul_f32 v[48:49], v[48:49], v[228:229] op_sel_hi:[1,0]
	v_lshlrev_b32_e32 v238, 16, v230
	v_and_b32_e32 v239, 0xffff0000, v230
	v_lshlrev_b32_e32 v240, 16, v231
	v_and_b32_e32 v241, 0xffff0000, v231
	v_mul_f32_e32 v242, 0xbfb8aa3b, v238
	v_mul_f32_e32 v243, 0xbfb8aa3b, v239
	v_mul_f32_e32 v244, 0xbfb8aa3b, v240
	v_mul_f32_e32 v245, 0xbfb8aa3b, v241
	v_exp_f32_e32 v242, v242
	v_exp_f32_e32 v243, v243
	v_exp_f32_e32 v244, v244
	v_exp_f32_e32 v245, v245
	v_add_f32_e32 v242, 1.0, v242
	v_add_f32_e32 v243, 1.0, v243
	v_add_f32_e32 v244, 1.0, v244
	v_add_f32_e32 v245, 1.0, v245
	v_rcp_f32_e32 v242, v242
	v_rcp_f32_e32 v243, v243
	v_rcp_f32_e32 v244, v244
	v_rcp_f32_e32 v245, v245
	v_mul_f32_e32 v242, v242, v238
	v_mul_f32_e32 v243, v243, v239
	v_mul_f32_e32 v244, v244, v240
	v_mul_f32_e32 v245, v245, v241
	v_mul_f32_e32 v46, v242, v46
	v_mul_f32_e32 v47, v243, v47
	v_mul_f32_e32 v48, v244, v48
	v_mul_f32_e32 v49, v245, v49
	v_cvt_pk_bf16_f32 v230, v46, v47
	v_cvt_pk_bf16_f32 v231, v48, v49
	v_pk_mul_f32 v[42:43], v[42:43], v[228:229] op_sel_hi:[1,0]
	v_pk_mul_f32 v[44:45], v[44:45], v[228:229] op_sel_hi:[1,0]
	v_lshlrev_b32_e32 v238, 16, v232
	v_and_b32_e32 v239, 0xffff0000, v232
	v_lshlrev_b32_e32 v240, 16, v233
	v_and_b32_e32 v241, 0xffff0000, v233
	v_mul_f32_e32 v242, 0xbfb8aa3b, v238
	v_mul_f32_e32 v243, 0xbfb8aa3b, v239
	v_mul_f32_e32 v244, 0xbfb8aa3b, v240
	v_mul_f32_e32 v245, 0xbfb8aa3b, v241
	v_exp_f32_e32 v242, v242
	v_exp_f32_e32 v243, v243
	v_exp_f32_e32 v244, v244
	v_exp_f32_e32 v245, v245
	v_add_f32_e32 v242, 1.0, v242
	v_add_f32_e32 v243, 1.0, v243
	v_add_f32_e32 v244, 1.0, v244
	v_add_f32_e32 v245, 1.0, v245
	v_rcp_f32_e32 v242, v242
	v_rcp_f32_e32 v243, v243
	v_rcp_f32_e32 v244, v244
	v_rcp_f32_e32 v245, v245
	v_mul_f32_e32 v242, v242, v238
	v_mul_f32_e32 v243, v243, v239
	v_mul_f32_e32 v244, v244, v240
	v_mul_f32_e32 v245, v245, v241
	v_mul_f32_e32 v42, v242, v42
	v_mul_f32_e32 v43, v243, v43
	v_mul_f32_e32 v44, v244, v44
	v_mul_f32_e32 v45, v245, v45
	v_cvt_pk_bf16_f32 v232, v42, v43
	v_cvt_pk_bf16_f32 v233, v44, v45
	v_pk_mul_f32 v[38:39], v[38:39], v[228:229] op_sel_hi:[1,0]
	v_pk_mul_f32 v[40:41], v[40:41], v[228:229] op_sel_hi:[1,0]
	v_lshlrev_b32_e32 v238, 16, v234
	v_and_b32_e32 v239, 0xffff0000, v234
	v_lshlrev_b32_e32 v240, 16, v235
	v_and_b32_e32 v241, 0xffff0000, v235
	v_mul_f32_e32 v242, 0xbfb8aa3b, v238
	v_mul_f32_e32 v243, 0xbfb8aa3b, v239
	v_mul_f32_e32 v244, 0xbfb8aa3b, v240
	v_mul_f32_e32 v245, 0xbfb8aa3b, v241
	v_exp_f32_e32 v242, v242
	v_exp_f32_e32 v243, v243
	v_exp_f32_e32 v244, v244
	v_exp_f32_e32 v245, v245
	v_add_f32_e32 v242, 1.0, v242
	v_add_f32_e32 v243, 1.0, v243
	v_add_f32_e32 v244, 1.0, v244
	v_add_f32_e32 v245, 1.0, v245
	v_rcp_f32_e32 v242, v242
	v_rcp_f32_e32 v243, v243
	v_rcp_f32_e32 v244, v244
	v_rcp_f32_e32 v245, v245
	v_mul_f32_e32 v242, v242, v238
	v_mul_f32_e32 v243, v243, v239
	v_mul_f32_e32 v244, v244, v240
	v_mul_f32_e32 v245, v245, v241
	v_mul_f32_e32 v38, v242, v38
	v_mul_f32_e32 v39, v243, v39
	v_mul_f32_e32 v40, v244, v40
	v_mul_f32_e32 v41, v245, v41
	v_cvt_pk_bf16_f32 v234, v38, v39
	v_cvt_pk_bf16_f32 v235, v40, v41
	v_pk_mul_f32 v[34:35], v[34:35], v[228:229] op_sel_hi:[1,0]
	v_pk_mul_f32 v[36:37], v[36:37], v[228:229] op_sel_hi:[1,0]
	v_lshlrev_b32_e32 v238, 16, v236
	v_and_b32_e32 v239, 0xffff0000, v236
	v_lshlrev_b32_e32 v240, 16, v237
	v_and_b32_e32 v241, 0xffff0000, v237
	v_mul_f32_e32 v242, 0xbfb8aa3b, v238
	v_mul_f32_e32 v243, 0xbfb8aa3b, v239
	v_mul_f32_e32 v244, 0xbfb8aa3b, v240
	v_mul_f32_e32 v245, 0xbfb8aa3b, v241
	v_exp_f32_e32 v242, v242
	v_exp_f32_e32 v243, v243
	v_exp_f32_e32 v244, v244
	v_exp_f32_e32 v245, v245
	v_add_f32_e32 v242, 1.0, v242
	v_add_f32_e32 v243, 1.0, v243
	v_add_f32_e32 v244, 1.0, v244
	v_add_f32_e32 v245, 1.0, v245
	v_rcp_f32_e32 v242, v242
	v_rcp_f32_e32 v243, v243
	v_rcp_f32_e32 v244, v244
	v_rcp_f32_e32 v245, v245
	v_mul_f32_e32 v242, v242, v238
	v_mul_f32_e32 v243, v243, v239
	v_mul_f32_e32 v244, v244, v240
	v_mul_f32_e32 v245, v245, v241
	v_mul_f32_e32 v34, v242, v34
	v_mul_f32_e32 v35, v243, v35
	v_mul_f32_e32 v36, v244, v36
	v_mul_f32_e32 v37, v245, v37
	v_cvt_pk_bf16_f32 v236, v34, v35
	v_cvt_pk_bf16_f32 v237, v36, v37
	ds_write_b64 v248, v[230:231]
	ds_write_b64 v249, v[232:233]
	ds_write_b64 v250, v[234:235]
	ds_write_b64 v251, v[236:237]
	ds_read_b128 v[46:49], v196
	ds_read_b128 v[42:45], v196 offset:1024
	s_waitcnt vmcnt(20)
	ds_write_b128 v196, v[180:183]
	ds_write_b128 v196, v[184:187] offset:1024
	ds_read_b64 v[230:231], v248
	ds_read_b64 v[232:233], v249
	ds_read_b64 v[234:235], v250
	ds_read_b64 v[236:237], v251
	s_waitcnt lgkmcnt(4)
	global_store_dwordx4 v[220:221], v[46:49], off offset:384
	global_store_dwordx4 v[224:225], v[42:45], off offset:384
	s_waitcnt lgkmcnt(0)
; __device__ __forceinline__ unsigned cvt_pk_bf16(float lo, float hi) { unsigned r; asm("v_cvt_pk_bf16_f32 %0, %1, %2" : "=v"(r) : "v"(lo), "v"(hi)); return r; }
; __device__ __forceinline__ float silu_f(float x) { return x * __builtin_amdgcn_rcpf(1.f + __builtin_amdgcn_exp2f(-LOG2E * x)); }
; __device__ __forceinline__ void attn_phase(const Params& p, LAS unsigned char* lds, int li, int tid, int G, bf16_t* __restrict__ dst, const bf16_t* __restrict__ ZGA) {
;     ...
; #pragma unroll
;         for (int mb = 0; mb < 3; ++mb) {
;             const int hh = mb, r = 16 * w + lq;
;             const size_t tok = (size_t)(t0 + r); const int hcol = (3 * hk + hh) * 128 + 4 * g;
;             float lt = lrun[mb]; lt += __shfl_xor(lt, 16); lt += __shfl_xor(lt, 32);
;             lt += __builtin_amdgcn_exp2f(BS[hh * 260 + 257]);
;             const float inv = 1.f / lt;
; #pragma unroll
;             for (int db = 0; db < 8; ++db) {
;                 const f32x4 o = oacc[mb][db] * inv;
;                 u32x2 wv; wv.x = cvt_pk_bf16(o[0] * silu_f(bf_lo(gv[mb][db].x)), o[1] * silu_f(bf_hi(gv[mb][db].x))); wv.y = cvt_pk_bf16(o[2] * silu_f(bf_lo(gv[mb][db].y)), o[3] * silu_f(bf_hi(gv[mb][db].y)));
;                 *(u32x2*)(dst + tok * 2048 + hcol + 16 * db) = wv;
;             }
;         }
	v_pk_mul_f32 v[30:31], v[30:31], v[246:247] op_sel_hi:[1,0]
	v_pk_mul_f32 v[32:33], v[32:33], v[246:247] op_sel_hi:[1,0]
	v_lshlrev_b32_e32 v238, 16, v230
	v_and_b32_e32 v239, 0xffff0000, v230
	v_lshlrev_b32_e32 v240, 16, v231
	v_and_b32_e32 v241, 0xffff0000, v231
	v_mul_f32_e32 v242, 0xbfb8aa3b, v238
	v_mul_f32_e32 v243, 0xbfb8aa3b, v239
	v_mul_f32_e32 v244, 0xbfb8aa3b, v240
	v_mul_f32_e32 v245, 0xbfb8aa3b, v241
	v_exp_f32_e32 v242, v242
	v_exp_f32_e32 v243, v243
	v_exp_f32_e32 v244, v244
	v_exp_f32_e32 v245, v245
	v_add_f32_e32 v242, 1.0, v242
	v_add_f32_e32 v243, 1.0, v243
	v_add_f32_e32 v244, 1.0, v244
	v_add_f32_e32 v245, 1.0, v245
	v_rcp_f32_e32 v242, v242
	v_rcp_f32_e32 v243, v243
	v_rcp_f32_e32 v244, v244
	v_rcp_f32_e32 v245, v245
	v_mul_f32_e32 v242, v242, v238
	v_mul_f32_e32 v243, v243, v239
	v_mul_f32_e32 v244, v244, v240
	v_mul_f32_e32 v245, v245, v241
	v_mul_f32_e32 v30, v242, v30
	v_mul_f32_e32 v31, v243, v31
	v_mul_f32_e32 v32, v244, v32
	v_mul_f32_e32 v33, v245, v33
	v_cvt_pk_bf16_f32 v230, v30, v31
	v_cvt_pk_bf16_f32 v231, v32, v33
	v_pk_mul_f32 v[26:27], v[26:27], v[246:247] op_sel_hi:[1,0]
	v_pk_mul_f32 v[28:29], v[28:29], v[246:247] op_sel_hi:[1,0]
	v_lshlrev_b32_e32 v238, 16, v232
	v_and_b32_e32 v239, 0xffff0000, v232
	v_lshlrev_b32_e32 v240, 16, v233
	v_and_b32_e32 v241, 0xffff0000, v233
	v_mul_f32_e32 v242, 0xbfb8aa3b, v238
	v_mul_f32_e32 v243, 0xbfb8aa3b, v239
	v_mul_f32_e32 v244, 0xbfb8aa3b, v240
	v_mul_f32_e32 v245, 0xbfb8aa3b, v241
	v_exp_f32_e32 v242, v242
	v_exp_f32_e32 v243, v243
	v_exp_f32_e32 v244, v244
	v_exp_f32_e32 v245, v245
	v_add_f32_e32 v242, 1.0, v242
	v_add_f32_e32 v243, 1.0, v243
	v_add_f32_e32 v244, 1.0, v244
	v_add_f32_e32 v245, 1.0, v245
	v_rcp_f32_e32 v242, v242
	v_rcp_f32_e32 v243, v243
	v_rcp_f32_e32 v244, v244
	v_rcp_f32_e32 v245, v245
	v_mul_f32_e32 v242, v242, v238
	v_mul_f32_e32 v243, v243, v239
	v_mul_f32_e32 v244, v244, v240
	v_mul_f32_e32 v245, v245, v241
	v_mul_f32_e32 v26, v242, v26
	v_mul_f32_e32 v27, v243, v27
	v_mul_f32_e32 v28, v244, v28
	v_mul_f32_e32 v29, v245, v29
	v_cvt_pk_bf16_f32 v232, v26, v27
	v_cvt_pk_bf16_f32 v233, v28, v29
	v_pk_mul_f32 v[22:23], v[22:23], v[246:247] op_sel_hi:[1,0]
	v_pk_mul_f32 v[24:25], v[24:25], v[246:247] op_sel_hi:[1,0]
	v_lshlrev_b32_e32 v238, 16, v234
	v_and_b32_e32 v239, 0xffff0000, v234
	v_lshlrev_b32_e32 v240, 16, v235
	v_and_b32_e32 v241, 0xffff0000, v235
	v_mul_f32_e32 v242, 0xbfb8aa3b, v238
	v_mul_f32_e32 v243, 0xbfb8aa3b, v239
	v_mul_f32_e32 v244, 0xbfb8aa3b, v240
	v_mul_f32_e32 v245, 0xbfb8aa3b, v241
	v_exp_f32_e32 v242, v242
	v_exp_f32_e32 v243, v243
	v_exp_f32_e32 v244, v244
	v_exp_f32_e32 v245, v245
	v_add_f32_e32 v242, 1.0, v242
	v_add_f32_e32 v243, 1.0, v243
	v_add_f32_e32 v244, 1.0, v244
	v_add_f32_e32 v245, 1.0, v245
	v_rcp_f32_e32 v242, v242
	v_rcp_f32_e32 v243, v243
	v_rcp_f32_e32 v244, v244
	v_rcp_f32_e32 v245, v245
	v_mul_f32_e32 v242, v242, v238
	v_mul_f32_e32 v243, v243, v239
	v_mul_f32_e32 v244, v244, v240
	v_mul_f32_e32 v245, v245, v241
	v_mul_f32_e32 v22, v242, v22
	v_mul_f32_e32 v23, v243, v23
	v_mul_f32_e32 v24, v244, v24
	v_mul_f32_e32 v25, v245, v25
	v_cvt_pk_bf16_f32 v234, v22, v23
	v_cvt_pk_bf16_f32 v235, v24, v25
	v_pk_mul_f32 v[18:19], v[18:19], v[246:247] op_sel_hi:[1,0]
	v_pk_mul_f32 v[20:21], v[20:21], v[246:247] op_sel_hi:[1,0]
	v_lshlrev_b32_e32 v238, 16, v236
	v_and_b32_e32 v239, 0xffff0000, v236
	v_lshlrev_b32_e32 v240, 16, v237
	v_and_b32_e32 v241, 0xffff0000, v237
	v_mul_f32_e32 v242, 0xbfb8aa3b, v238
	v_mul_f32_e32 v243, 0xbfb8aa3b, v239
	v_mul_f32_e32 v244, 0xbfb8aa3b, v240
	v_mul_f32_e32 v245, 0xbfb8aa3b, v241
	v_exp_f32_e32 v242, v242
	v_exp_f32_e32 v243, v243
	v_exp_f32_e32 v244, v244
	v_exp_f32_e32 v245, v245
	v_add_f32_e32 v242, 1.0, v242
	v_add_f32_e32 v243, 1.0, v243
	v_add_f32_e32 v244, 1.0, v244
	v_add_f32_e32 v245, 1.0, v245
	v_rcp_f32_e32 v242, v242
	v_rcp_f32_e32 v243, v243
	v_rcp_f32_e32 v244, v244
	v_rcp_f32_e32 v245, v245
	v_mul_f32_e32 v242, v242, v238
	v_mul_f32_e32 v243, v243, v239
	v_mul_f32_e32 v244, v244, v240
	v_mul_f32_e32 v245, v245, v241
	v_mul_f32_e32 v18, v242, v18
	v_mul_f32_e32 v19, v243, v19
	v_mul_f32_e32 v20, v244, v20
	v_mul_f32_e32 v21, v245, v21
	v_cvt_pk_bf16_f32 v236, v18, v19
	v_cvt_pk_bf16_f32 v237, v20, v21
	ds_write_b64 v248, v[230:231]
	ds_write_b64 v249, v[232:233]
	ds_write_b64 v250, v[234:235]
	ds_write_b64 v251, v[236:237]
	ds_read_b128 v[30:33], v196
	ds_read_b128 v[26:29], v196 offset:1024
	s_waitcnt vmcnt(20)
	ds_write_b128 v196, v[188:191]
	ds_write_b128 v196, v[192:195] offset:1024
	ds_read_b64 v[230:231], v248
	ds_read_b64 v[232:233], v249
	ds_read_b64 v[234:235], v250
	ds_read_b64 v[236:237], v251
	s_waitcnt lgkmcnt(4)
; __device__ __forceinline__ unsigned cvt_pk_bf16(float lo, float hi) { unsigned r; asm("v_cvt_pk_bf16_f32 %0, %1, %2" : "=v"(r) : "v"(lo), "v"(hi)); return r; }
; __device__ __forceinline__ float silu_f(float x) { return x * __builtin_amdgcn_rcpf(1.f + __builtin_amdgcn_exp2f(-LOG2E * x)); }
; __device__ __forceinline__ void attn_phase(const Params& p, LAS unsigned char* lds, int li, int tid, int G, bf16_t* __restrict__ dst, const bf16_t* __restrict__ ZGA) {
;     ...
;     for (int kround = 0; kround < icnt; ++kround) {
;         const int item = ibase + kround * istep;
;         const int nitem = (kround + 1 < icnt) ? item + istep : -1;
;     ...
; #pragma unroll
;         for (int mb = 0; mb < 3; ++mb) {
;             const int hh = mb, r = 16 * w + lq;
;             const size_t tok = (size_t)(t0 + r); const int hcol = (3 * hk + hh) * 128 + 4 * g;
;             float lt = lrun[mb]; lt += __shfl_xor(lt, 16); lt += __shfl_xor(lt, 32);
;             lt += __builtin_amdgcn_exp2f(BS[hh * 260 + 257]);
;             const float inv = 1.f / lt;
; #pragma unroll
;             for (int db = 0; db < 8; ++db) {
;                 const f32x4 o = oacc[mb][db] * inv;
;                 u32x2 wv; wv.x = cvt_pk_bf16(o[0] * silu_f(bf_lo(gv[mb][db].x)), o[1] * silu_f(bf_hi(gv[mb][db].x))); wv.y = cvt_pk_bf16(o[2] * silu_f(bf_lo(gv[mb][db].y)), o[3] * silu_f(bf_hi(gv[mb][db].y)));
;                 *(u32x2*)(dst + tok * 2048 + hcol + 16 * db) = wv;
;             }
;         }
	global_store_dwordx4 v[220:221], v[30:33], off offset:512
	global_store_dwordx4 v[224:225], v[26:29], off offset:512
	s_waitcnt lgkmcnt(0)
	v_pk_mul_f32 v[14:15], v[14:15], v[246:247] op_sel_hi:[1,0]
	v_pk_mul_f32 v[16:17], v[16:17], v[246:247] op_sel_hi:[1,0]
	v_lshlrev_b32_e32 v238, 16, v230
	v_and_b32_e32 v239, 0xffff0000, v230
	v_lshlrev_b32_e32 v240, 16, v231
	v_and_b32_e32 v241, 0xffff0000, v231
	v_mul_f32_e32 v242, 0xbfb8aa3b, v238
	v_mul_f32_e32 v243, 0xbfb8aa3b, v239
	v_mul_f32_e32 v244, 0xbfb8aa3b, v240
	v_mul_f32_e32 v245, 0xbfb8aa3b, v241
	v_exp_f32_e32 v242, v242
	v_exp_f32_e32 v243, v243
	v_exp_f32_e32 v244, v244
	v_exp_f32_e32 v245, v245
	v_add_f32_e32 v242, 1.0, v242
	v_add_f32_e32 v243, 1.0, v243
	v_add_f32_e32 v244, 1.0, v244
	v_add_f32_e32 v245, 1.0, v245
	v_rcp_f32_e32 v242, v242
	v_rcp_f32_e32 v243, v243
	v_rcp_f32_e32 v244, v244
	v_rcp_f32_e32 v245, v245
	v_mul_f32_e32 v242, v242, v238
	v_mul_f32_e32 v243, v243, v239
	v_mul_f32_e32 v244, v244, v240
	v_mul_f32_e32 v245, v245, v241
	v_mul_f32_e32 v14, v242, v14
	v_mul_f32_e32 v15, v243, v15
	v_mul_f32_e32 v16, v244, v16
	v_mul_f32_e32 v17, v245, v17
	v_cvt_pk_bf16_f32 v230, v14, v15
	v_cvt_pk_bf16_f32 v231, v16, v17
	v_pk_mul_f32 v[10:11], v[10:11], v[246:247] op_sel_hi:[1,0]
	v_pk_mul_f32 v[12:13], v[12:13], v[246:247] op_sel_hi:[1,0]
	v_lshlrev_b32_e32 v238, 16, v232
	v_and_b32_e32 v239, 0xffff0000, v232
	v_lshlrev_b32_e32 v240, 16, v233
	v_and_b32_e32 v241, 0xffff0000, v233
	v_mul_f32_e32 v242, 0xbfb8aa3b, v238
	v_mul_f32_e32 v243, 0xbfb8aa3b, v239
	v_mul_f32_e32 v244, 0xbfb8aa3b, v240
	v_mul_f32_e32 v245, 0xbfb8aa3b, v241
	v_exp_f32_e32 v242, v242
	v_exp_f32_e32 v243, v243
	v_exp_f32_e32 v244, v244
	v_exp_f32_e32 v245, v245
	v_add_f32_e32 v242, 1.0, v242
	v_add_f32_e32 v243, 1.0, v243
	v_add_f32_e32 v244, 1.0, v244
	v_add_f32_e32 v245, 1.0, v245
	v_rcp_f32_e32 v242, v242
	v_rcp_f32_e32 v243, v243
	v_rcp_f32_e32 v244, v244
	v_rcp_f32_e32 v245, v245
	v_mul_f32_e32 v242, v242, v238
	v_mul_f32_e32 v243, v243, v239
	v_mul_f32_e32 v244, v244, v240
	v_mul_f32_e32 v245, v245, v241
	v_mul_f32_e32 v10, v242, v10
	v_mul_f32_e32 v11, v243, v11
	v_mul_f32_e32 v12, v244, v12
	v_mul_f32_e32 v13, v245, v13
	v_cvt_pk_bf16_f32 v232, v10, v11
	v_cvt_pk_bf16_f32 v233, v12, v13
	v_pk_mul_f32 v[6:7], v[6:7], v[246:247] op_sel_hi:[1,0]
	v_pk_mul_f32 v[8:9], v[8:9], v[246:247] op_sel_hi:[1,0]
	v_lshlrev_b32_e32 v238, 16, v234
	v_and_b32_e32 v239, 0xffff0000, v234
	v_lshlrev_b32_e32 v240, 16, v235
	v_and_b32_e32 v241, 0xffff0000, v235
	v_mul_f32_e32 v242, 0xbfb8aa3b, v238
	v_mul_f32_e32 v243, 0xbfb8aa3b, v239
	v_mul_f32_e32 v244, 0xbfb8aa3b, v240
	v_mul_f32_e32 v245, 0xbfb8aa3b, v241
	v_exp_f32_e32 v242, v242
	v_exp_f32_e32 v243, v243
	v_exp_f32_e32 v244, v244
	v_exp_f32_e32 v245, v245
	v_add_f32_e32 v242, 1.0, v242
	v_add_f32_e32 v243, 1.0, v243
	v_add_f32_e32 v244, 1.0, v244
	v_add_f32_e32 v245, 1.0, v245
	v_rcp_f32_e32 v242, v242
	v_rcp_f32_e32 v243, v243
	v_rcp_f32_e32 v244, v244
	v_rcp_f32_e32 v245, v245
	v_mul_f32_e32 v242, v242, v238
	v_mul_f32_e32 v243, v243, v239
	v_mul_f32_e32 v244, v244, v240
	v_mul_f32_e32 v245, v245, v241
	v_mul_f32_e32 v6, v242, v6
	v_mul_f32_e32 v7, v243, v7
	v_mul_f32_e32 v8, v244, v8
	v_mul_f32_e32 v9, v245, v9
	v_cvt_pk_bf16_f32 v234, v6, v7
	v_cvt_pk_bf16_f32 v235, v8, v9
	v_pk_mul_f32 v[2:3], v[2:3], v[246:247] op_sel_hi:[1,0]
	v_pk_mul_f32 v[4:5], v[4:5], v[246:247] op_sel_hi:[1,0]
	v_lshlrev_b32_e32 v238, 16, v236
	v_and_b32_e32 v239, 0xffff0000, v236
	v_lshlrev_b32_e32 v240, 16, v237
	v_and_b32_e32 v241, 0xffff0000, v237
	v_mul_f32_e32 v242, 0xbfb8aa3b, v238
	v_mul_f32_e32 v243, 0xbfb8aa3b, v239
	v_mul_f32_e32 v244, 0xbfb8aa3b, v240
	v_mul_f32_e32 v245, 0xbfb8aa3b, v241
	v_exp_f32_e32 v242, v242
	v_exp_f32_e32 v243, v243
	v_exp_f32_e32 v244, v244
	v_exp_f32_e32 v245, v245
	v_add_f32_e32 v242, 1.0, v242
	v_add_f32_e32 v243, 1.0, v243
	v_add_f32_e32 v244, 1.0, v244
	v_add_f32_e32 v245, 1.0, v245
	v_rcp_f32_e32 v242, v242
	v_rcp_f32_e32 v243, v243
	v_rcp_f32_e32 v244, v244
	v_rcp_f32_e32 v245, v245
	v_mul_f32_e32 v242, v242, v238
	v_mul_f32_e32 v243, v243, v239
	v_mul_f32_e32 v244, v244, v240
	v_mul_f32_e32 v245, v245, v241
	v_mul_f32_e32 v2, v242, v2
	v_mul_f32_e32 v3, v243, v3
	v_mul_f32_e32 v4, v244, v4
	v_mul_f32_e32 v5, v245, v5
	v_cvt_pk_bf16_f32 v236, v2, v3
	v_cvt_pk_bf16_f32 v237, v4, v5
	ds_write_b64 v248, v[230:231]
	ds_write_b64 v249, v[232:233]
	ds_write_b64 v250, v[234:235]
	ds_write_b64 v251, v[236:237]
	ds_read_b128 v[14:17], v196
	ds_read_b128 v[10:13], v196 offset:1024
	s_waitcnt lgkmcnt(0)
	global_store_dwordx4 v[220:221], v[14:17], off offset:640
	global_store_dwordx4 v[224:225], v[10:13], off offset:640
	s_add_i32 s93, s93, s2
	s_cmp_eq_u32 s95, s14
	s_cbranch_scc1 .LBB0_367

; __device__ __forceinline__ void attn_phase(const Params& p, LAS unsigned char* lds, int li, int tid, int G, bf16_t* __restrict__ dst, const bf16_t* __restrict__ ZGA) {
;     ...
;         bf16x8 Qf[3][4];
;         {
;             const float* qg = p.q_gain + li * 128; const float* kg = p.k_gain + li * 128;
; #pragma unroll
;             for (int mb = 0; mb < 3; ++mb) {
;                 u32x4 raw[4]; float ss = 0.f;
; #pragma unroll
;                 for (int ks = 0; ks < 4; ++ks) { raw[ks] = qraw[mb][ks];
; #pragma unroll
;                     for (int e = 0; e < 4; ++e) { const float a = bf_lo(raw[ks][e]), b = bf_hi(raw[ks][e]); ss += a * a + b * b; } }
;                 ss += __shfl_xor(ss, 16); ss += __shfl_xor(ss, 32);
;                 const float rq = rsqrtf(ss * (1.f / 128.f) + EPS) * (0.08838834764831845f * LOG2E);
; #pragma unroll
;                 for (int ks = 0; ks < 4; ++ks) {
;                     const f32x4 g0 = *(const f32x4*)(qg + 32 * ks + 8 * g) * *(const f32x4*)(kg + 32 * ks + 8 * g), g1 = *(const f32x4*)(qg + 32 * ks + 8 * g + 4) * *(const f32x4*)(kg + 32 * ks + 8 * g + 4);
.LBB0_323:
	s_waitcnt vmcnt(0)
	v_mbcnt_lo_u32_b32 v2, -1, 0
	v_mbcnt_hi_u32_b32 v2, -1, v2
	s_lshl_b32 s0, s35, 7
	s_add_i32 s0, s0, 0x21400
	v_lshrrev_b32_e32 v6, 3, v2
	v_and_b32_e32 v7, 7, v2
	v_xor_b32_e32 v7, v6, v7
	v_lshlrev_b32_e32 v7, 4, v7
	v_lshl_add_u32 v3, v6, 7, v7
	v_add_u32_e32 v3, s0, v3
	v_and_b32_e32 v6, 15, v2
	v_lshrrev_b32_e32 v7, 4, v2
	v_xor_b32_e32 v7, v7, v6
	v_and_b32_e32 v7, 3, v7
	v_lshlrev_b32_e32 v7, 4, v7
	v_lshl_add_u32 v4, v6, 7, v7
	v_bfe_u32 v7, v6, 2, 1
	v_lshl_add_u32 v4, v7, 6, v4
	v_add_u32_e32 v4, s0, v4
	v_xor_b32_e32 v5, 64, v4
	ds_write_b128 v3, v[136:139]
	ds_write_b128 v3, v[106:109] offset:1024
	ds_read_b128 v[136:139], v4
	ds_read_b128 v[106:109], v5
	ds_write_b128 v3, v[102:105]
	ds_write_b128 v3, v[98:101] offset:1024
	ds_read_b128 v[102:105], v4
	ds_read_b128 v[98:101], v5
	ds_write_b128 v3, v[124:127]
	ds_write_b128 v3, v[120:123] offset:1024
	ds_read_b128 v[124:127], v4
	ds_read_b128 v[120:123], v5
	ds_write_b128 v3, v[116:119]
	ds_write_b128 v3, v[112:115] offset:1024
	ds_read_b128 v[116:119], v4
	ds_read_b128 v[112:115], v5
	ds_write_b128 v3, v[132:135]
	ds_write_b128 v3, v[128:131] offset:1024
	ds_read_b128 v[132:135], v4
	ds_read_b128 v[128:131], v5
	ds_write_b128 v3, v[144:147]
	ds_write_b128 v3, v[140:143] offset:1024
	ds_read_b128 v[144:147], v4
	ds_read_b128 v[140:143], v5
	s_waitcnt lgkmcnt(0)
	v_and_b32_e32 v27, 0xffff0000, v136
	v_and_b32_e32 v95, 0xffff0000, v137
	v_lshlrev_b32_e32 v26, 16, v136
	v_mul_f32_e32 v6, v27, v27
	v_lshlrev_b32_e32 v94, 16, v137
	v_mul_f32_e32 v7, v95, v95
	v_fmac_f32_e32 v6, v26, v26
	v_fmac_f32_e32 v7, v94, v94
	v_and_b32_e32 v97, 0xffff0000, v138
	v_and_b32_e32 v3, 64, v202
	v_add_f32_e32 v6, v6, v7
	v_lshlrev_b32_e32 v96, 16, v138
	v_mul_f32_e32 v7, v97, v97
	v_ashrrev_i32_e32 v38, 4, v0
	v_xor_b32_e32 v2, 16, v202
	v_add_u32_e32 v39, 64, v3
	v_fmac_f32_e32 v7, v96, v96
	v_and_b32_e32 v111, 0xffff0000, v139
	v_cmp_lt_i32_e32 vcc, v2, v39
	v_lshlrev_b32_e32 v172, 3, v38
	v_add_f32_e32 v6, v7, v6
	v_lshlrev_b32_e32 v110, 16, v139
	v_mul_f32_e32 v7, v111, v111
	v_cndmask_b32_e32 v2, v202, v2, vcc
	v_ashrrev_i32_e32 v173, 31, v172
	v_fmac_f32_e32 v7, v110, v110
	v_lshlrev_b32_e32 v136, 16, v106
	v_and_b32_e32 v106, 0xffff0000, v106
	v_lshlrev_b32_e32 v204, 2, v2
	v_lshlrev_b64 v[2:3], 2, v[172:173]
	v_add_f32_e32 v6, v7, v6
	v_mul_f32_e32 v7, v106, v106
	s_waitcnt lgkmcnt(0)
	v_lshl_add_u64 v[4:5], s[8:9], 0, v[2:3]
	v_fmac_f32_e32 v7, v136, v136
	v_lshl_add_u64 v[2:3], s[10:11], 0, v[2:3]
	v_add_f32_e32 v14, v7, v6
	global_load_dwordx4 v[6:9], v[4:5], off offset:16
	global_load_dwordx4 v[10:13], v[4:5], off
	global_load_dwordx4 v[16:19], v[2:3], off offset:16
	global_load_dwordx4 v[20:23], v[2:3], off
	global_load_dwordx4 v[28:31], v[4:5], off offset:144
	global_load_dwordx4 v[40:43], v[4:5], off offset:128
	global_load_dwordx4 v[44:47], v[2:3], off offset:144
	global_load_dwordx4 v[48:51], v[2:3], off offset:128
	global_load_dwordx4 v[52:55], v[4:5], off offset:272
	global_load_dwordx4 v[56:59], v[4:5], off offset:256
	global_load_dwordx4 v[60:63], v[2:3], off offset:272
	global_load_dwordx4 v[64:67], v[2:3], off offset:256
	global_load_dwordx4 v[68:71], v[4:5], off offset:400
	global_load_dwordx4 v[72:75], v[4:5], off offset:384
	global_load_dwordx4 v[76:79], v[2:3], off offset:400
	global_load_dwordx4 v[80:83], v[2:3], off offset:384
	v_lshlrev_b32_e32 v137, 16, v107
	v_and_b32_e32 v107, 0xffff0000, v107
	v_mul_f32_e32 v15, v107, v107
	v_fmac_f32_e32 v15, v137, v137
	v_lshlrev_b32_e32 v138, 16, v108
	v_and_b32_e32 v108, 0xffff0000, v108
	v_add_f32_e32 v14, v15, v14
	v_mul_f32_e32 v15, v108, v108
	v_fmac_f32_e32 v15, v138, v138
	v_lshlrev_b32_e32 v139, 16, v109
	v_and_b32_e32 v109, 0xffff0000, v109
	v_add_f32_e32 v14, v15, v14
	v_mul_f32_e32 v15, v109, v109
	v_fmac_f32_e32 v15, v139, v139
	v_and_b32_e32 v85, 0xffff0000, v103
	v_and_b32_e32 v84, 0xffff0000, v102
	v_add_f32_e32 v24, v15, v14
	v_lshlrev_b32_e32 v33, 16, v103
	v_lshlrev_b32_e32 v32, 16, v102
	v_pk_mul_f32 v[14:15], v[84:85], v[84:85]
	v_and_b32_e32 v89, 0xffff0000, v105
	v_pk_fma_f32 v[14:15], v[32:33], v[32:33], v[14:15]
	v_and_b32_e32 v88, 0xffff0000, v104
	v_add_f32_e32 v14, v14, v24
	v_add_f32_e32 v24, v15, v14
	v_lshlrev_b32_e32 v87, 16, v105
	v_lshlrev_b32_e32 v86, 16, v104
	v_pk_mul_f32 v[14:15], v[88:89], v[88:89]
	v_and_b32_e32 v93, 0xffff0000, v99
	v_pk_fma_f32 v[14:15], v[86:87], v[86:87], v[14:15]
	v_and_b32_e32 v92, 0xffff0000, v98
	v_add_f32_e32 v14, v14, v24
	v_add_f32_e32 v24, v15, v14
	v_lshlrev_b32_e32 v91, 16, v99
	v_lshlrev_b32_e32 v90, 16, v98
	v_pk_mul_f32 v[14:15], v[92:93], v[92:93]
	v_and_b32_e32 v35, 0xffff0000, v101
	v_pk_fma_f32 v[14:15], v[90:91], v[90:91], v[14:15]
	v_and_b32_e32 v34, 0xffff0000, v100
	v_add_f32_e32 v14, v14, v24
	v_add_f32_e32 v24, v15, v14
	v_lshlrev_b32_e32 v37, 16, v101
	v_lshlrev_b32_e32 v36, 16, v100
	v_pk_mul_f32 v[14:15], v[34:35], v[34:35]
	s_add_i32 s95, s95, 1
	v_pk_fma_f32 v[14:15], v[36:37], v[36:37], v[14:15]
	s_add_i32 s0, s34, s2
	v_add_f32_e32 v14, v14, v24
	v_add_f32_e32 v14, v15, v14
	ds_bpermute_b32 v15, v204, v14
	v_xor_b32_e32 v24, 32, v202
	v_cmp_lt_i32_e32 vcc, v24, v39
	s_cmp_lt_i32 s95, s14
	s_cselect_b32 s97, s0, -1
	v_cndmask_b32_e32 v24, v202, v24, vcc
	v_lshlrev_b32_e32 v205, 2, v24
	s_waitcnt lgkmcnt(0)
	v_add_f32_e32 v14, v14, v15
	ds_bpermute_b32 v15, v205, v14
	s_ashr_i32 s38, s34, 2
	s_cmpk_lt_i32 s38, 0x80
	s_cselect_b32 s0, 15, 31
	s_and_b32 s1, s0, s38
	s_waitcnt lgkmcnt(0)
; __device__ __forceinline__ unsigned cvt_pk_bf16(float lo, float hi) { unsigned r; asm("v_cvt_pk_bf16_f32 %0, %1, %2" : "=v"(r) : "v"(lo), "v"(hi)); return r; }
; __device__ __forceinline__ void attn_phase(const Params& p, LAS unsigned char* lds, int li, int tid, int G, bf16_t* __restrict__ dst, const bf16_t* __restrict__ ZGA) {
;     ...
;                 u32x4 raw[4]; float ss = 0.f;
; #pragma unroll
;                 for (int ks = 0; ks < 4; ++ks) { raw[ks] = qraw[mb][ks];
; #pragma unroll
;                     for (int e = 0; e < 4; ++e) { const float a = bf_lo(raw[ks][e]), b = bf_hi(raw[ks][e]); ss += a * a + b * b; } }
;                 ss += __shfl_xor(ss, 16); ss += __shfl_xor(ss, 32);
;                 const float rq = rsqrtf(ss * (1.f / 128.f) + EPS) * (0.08838834764831845f * LOG2E);
; #pragma unroll
;                 for (int ks = 0; ks < 4; ++ks) {
;                     const f32x4 g0 = *(const f32x4*)(qg + 32 * ks + 8 * g) * *(const f32x4*)(kg + 32 * ks + 8 * g), g1 = *(const f32x4*)(qg + 32 * ks + 8 * g + 4) * *(const f32x4*)(kg + 32 * ks + 8 * g + 4);
;                     u32x4 o;
;                     o.x = cvt_pk_bf16(bf_lo(raw[ks].x) * rq * g0[0], bf_hi(raw[ks].x) * rq * g0[1]);
;                     o.y = cvt_pk_bf16(bf_lo(raw[ks].y) * rq * g0[2], bf_hi(raw[ks].y) * rq * g0[3]);
;                     o.z = cvt_pk_bf16(bf_lo(raw[ks].z) * rq * g1[0], bf_hi(raw[ks].z) * rq * g1[1]);
;                     o.w = cvt_pk_bf16(bf_lo(raw[ks].w) * rq * g1[2], bf_hi(raw[ks].w) * rq * g1[3]);
;                     Qf[mb][ks] = __builtin_bit_cast(bf16x8, o);
;                 }
	v_add_f32_e32 v14, v14, v15
	v_fmamk_f32 v14, v14, 0x3c000000, v201
	v_mul_f32_e32 v15, 0x4b800000, v14
	v_cmp_gt_f32_e32 vcc, s87, v14
	s_cmp_lg_u32 s1, s0
	s_cselect_b64 s[4:5], -1, 0
	v_cndmask_b32_e32 v14, v14, v15, vcc
	v_rsq_f32_e32 v2, v14
	s_cmp_lg_u32 s1, 0
	s_cselect_b64 s[48:49], -1, 0
	s_and_b64 s[18:19], s[48:49], exec
	v_mul_f32_e32 v3, 0x45800000, v2
	v_cndmask_b32_e32 v2, v2, v3, vcc
	v_mul_f32_e32 v148, 0x3e0293ee, v2
	s_waitcnt vmcnt(12)
	v_pk_mul_f32 v[24:25], v[10:11], v[20:21]
	v_mul_f32_e32 v4, v148, v26
	v_mul_f32_e32 v5, v148, v27
	v_mul_f32_e32 v4, v24, v4
	v_mul_f32_e32 v5, v25, v5
	v_pk_mul_f32 v[14:15], v[12:13], v[22:23]
	v_pk_mul_f32 v[2:3], v[8:9], v[18:19]
	v_pk_mul_f32 v[8:9], v[6:7], v[16:17]
	v_cvt_pk_bf16_f32 v98, v4, v5
	v_mul_f32_e32 v4, v148, v94
	v_mul_f32_e32 v5, v148, v95
	s_waitcnt vmcnt(8)
	v_pk_mul_f32 v[26:27], v[40:41], v[48:49]
	v_mul_f32_e32 v6, v148, v136
	v_mul_f32_e32 v7, v148, v106
	v_mul_f32_e32 v4, v14, v4
	v_mul_f32_e32 v5, v15, v5
	v_mul_f32_e32 v6, v6, v26
	v_mul_f32_e32 v7, v7, v27
	v_cvt_pk_bf16_f32 v99, v4, v5
	v_mul_f32_e32 v4, v148, v96
	v_mul_f32_e32 v5, v148, v97
	v_pk_mul_f32 v[16:17], v[42:43], v[50:51]
	v_cvt_pk_bf16_f32 v102, v6, v7
	v_mul_f32_e32 v6, v148, v137
	v_mul_f32_e32 v7, v148, v107
	v_mul_f32_e32 v4, v8, v4
	v_mul_f32_e32 v5, v9, v5
	v_pk_mul_f32 v[10:11], v[28:29], v[44:45]
	v_mul_f32_e32 v6, v6, v16
	v_mul_f32_e32 v7, v7, v17
	s_waitcnt vmcnt(4)
	v_pk_mul_f32 v[28:29], v[56:57], v[64:65]
	v_mul_f32_e32 v20, v148, v32
	v_cvt_pk_bf16_f32 v100, v4, v5
	v_mul_f32_e32 v4, v148, v110
	v_mul_f32_e32 v5, v148, v111
	v_cvt_pk_bf16_f32 v103, v6, v7
	v_mul_f32_e32 v6, v148, v138
	v_mul_f32_e32 v7, v148, v108
	v_mul_f32_e32 v20, v20, v28
	v_mul_f32_e32 v21, v148, v84
	v_mul_f32_e32 v4, v2, v4
	v_mul_f32_e32 v5, v3, v5
	v_mul_f32_e32 v6, v6, v10
	v_mul_f32_e32 v7, v7, v11
	v_mul_f32_e32 v21, v21, v29
	v_cvt_pk_bf16_f32 v106, v20, v21
	v_mul_f32_e32 v20, v148, v33
	s_waitcnt vmcnt(0)
	v_pk_mul_f32 v[32:33], v[72:73], v[80:81]
	v_mul_f32_e32 v40, v148, v90
	v_cvt_pk_bf16_f32 v101, v4, v5
	v_pk_mul_f32 v[4:5], v[30:31], v[46:47]
	v_cvt_pk_bf16_f32 v104, v6, v7
	v_mul_f32_e32 v6, v148, v139
	v_mul_f32_e32 v7, v148, v109
	v_mul_f32_e32 v40, v40, v32
	v_mul_f32_e32 v41, v148, v92
	v_mul_f32_e32 v6, v6, v4
	v_mul_f32_e32 v7, v7, v5
	v_pk_mul_f32 v[22:23], v[74:75], v[82:83]
	v_mul_f32_e32 v41, v41, v33
	v_cvt_pk_bf16_f32 v110, v40, v41
	v_mul_f32_e32 v40, v148, v91
	v_cvt_pk_bf16_f32 v105, v6, v7
	v_pk_mul_f32 v[18:19], v[58:59], v[66:67]
	v_pk_mul_f32 v[6:7], v[54:55], v[62:63]
	v_pk_mul_f32 v[12:13], v[52:53], v[60:61]
	v_mul_f32_e32 v58, v40, v22
	v_mul_f32_e32 v40, v148, v93
	v_and_b32_e32 v61, 0xffff0000, v124
	v_and_b32_e32 v63, 0xffff0000, v125
	v_mul_f32_e32 v59, v40, v23
	v_lshlrev_b32_e32 v60, 16, v124
	v_mul_f32_e32 v40, v61, v61
	v_lshlrev_b32_e32 v62, 16, v125
	v_mul_f32_e32 v41, v63, v63
	v_mul_f32_e32 v21, v148, v85
	v_fmac_f32_e32 v40, v60, v60
	v_fmac_f32_e32 v41, v62, v62
	v_and_b32_e32 v65, 0xffff0000, v126
	v_mul_f32_e32 v20, v20, v18
	v_mul_f32_e32 v21, v21, v19
	v_add_f32_e32 v40, v40, v41
	v_lshlrev_b32_e32 v64, 16, v126
	v_mul_f32_e32 v41, v65, v65
	v_cvt_pk_bf16_f32 v107, v20, v21
	v_mul_f32_e32 v20, v148, v86
	v_mul_f32_e32 v21, v148, v88
	v_fmac_f32_e32 v41, v64, v64
	v_and_b32_e32 v67, 0xffff0000, v127
	v_mul_f32_e32 v20, v20, v12
	v_mul_f32_e32 v21, v21, v13
	v_add_f32_e32 v40, v41, v40
	v_lshlrev_b32_e32 v66, 16, v127
	v_mul_f32_e32 v41, v67, v67
	v_cvt_pk_bf16_f32 v108, v20, v21
	v_mul_f32_e32 v20, v148, v87
	v_mul_f32_e32 v21, v148, v89
	v_pk_mul_f32 v[30:31], v[68:69], v[76:77]
	v_fmac_f32_e32 v41, v66, v66
	v_and_b32_e32 v69, 0xffff0000, v120
	v_mul_f32_e32 v20, v20, v6
	v_mul_f32_e32 v21, v21, v7
	v_add_f32_e32 v40, v41, v40
	v_lshlrev_b32_e32 v68, 16, v120
	v_mul_f32_e32 v41, v69, v69
	v_cvt_pk_bf16_f32 v109, v20, v21
	v_pk_mul_f32 v[20:21], v[70:71], v[78:79]
	v_fmac_f32_e32 v41, v68, v68
	v_and_b32_e32 v71, 0xffff0000, v121
	v_add_f32_e32 v40, v41, v40
	v_lshlrev_b32_e32 v70, 16, v121
	v_mul_f32_e32 v41, v71, v71
	v_fmac_f32_e32 v41, v70, v70
	v_and_b32_e32 v73, 0xffff0000, v122
	v_add_f32_e32 v40, v41, v40
	v_lshlrev_b32_e32 v72, 16, v122
	v_mul_f32_e32 v41, v73, v73
	v_fmac_f32_e32 v41, v72, v72
	v_and_b32_e32 v75, 0xffff0000, v123
	v_add_f32_e32 v40, v41, v40
	v_lshlrev_b32_e32 v74, 16, v123
	v_mul_f32_e32 v41, v75, v75
	v_fmac_f32_e32 v41, v74, v74
	v_and_b32_e32 v43, 0xffff0000, v117
	v_and_b32_e32 v42, 0xffff0000, v116
	v_add_f32_e32 v46, v41, v40
	v_lshlrev_b32_e32 v41, 16, v117
	v_lshlrev_b32_e32 v40, 16, v116
	v_pk_mul_f32 v[44:45], v[42:43], v[42:43]
	v_and_b32_e32 v47, 0xffff0000, v119
	v_pk_fma_f32 v[44:45], v[40:41], v[40:41], v[44:45]
	v_and_b32_e32 v51, 0xffff0000, v113
	v_add_f32_e32 v44, v44, v46
	v_and_b32_e32 v46, 0xffff0000, v118
	v_add_f32_e32 v50, v45, v44
	v_lshlrev_b32_e32 v45, 16, v119
	v_lshlrev_b32_e32 v44, 16, v118
	v_pk_mul_f32 v[48:49], v[46:47], v[46:47]
	v_and_b32_e32 v55, 0xffff0000, v115
	v_pk_fma_f32 v[48:49], v[44:45], v[44:45], v[48:49]
	v_mul_f32_e32 v36, v148, v36
	v_add_f32_e32 v48, v48, v50
	v_and_b32_e32 v50, 0xffff0000, v112
	v_add_f32_e32 v54, v49, v48
	v_lshlrev_b32_e32 v49, 16, v113
	v_lshlrev_b32_e32 v48, 16, v112
	v_pk_mul_f32 v[52:53], v[50:51], v[50:51]
	v_mul_f32_e32 v36, v36, v30
	v_pk_fma_f32 v[52:53], v[48:49], v[48:49], v[52:53]
	v_mul_f32_e32 v34, v148, v34
	v_add_f32_e32 v52, v52, v54
	v_and_b32_e32 v54, 0xffff0000, v114
	v_add_f32_e32 v76, v53, v52
	v_lshlrev_b32_e32 v53, 16, v115
	v_lshlrev_b32_e32 v52, 16, v114
	v_pk_mul_f32 v[56:57], v[54:55], v[54:55]
	v_mul_f32_e32 v34, v34, v31
	v_pk_fma_f32 v[56:57], v[52:53], v[52:53], v[56:57]
	v_cvt_pk_bf16_f32 v112, v36, v34
	v_mul_f32_e32 v34, v148, v37
	v_add_f32_e32 v56, v56, v76
	v_add_f32_e32 v56, v57, v56
	ds_bpermute_b32 v57, v204, v56
	v_mul_f32_e32 v34, v34, v20
	v_mul_f32_e32 v35, v148, v35
	v_mul_f32_e32 v35, v35, v21
	v_cvt_pk_bf16_f32 v113, v34, v35
	s_waitcnt lgkmcnt(0)
; __device__ __forceinline__ unsigned cvt_pk_bf16(float lo, float hi) { unsigned r; asm("v_cvt_pk_bf16_f32 %0, %1, %2" : "=v"(r) : "v"(lo), "v"(hi)); return r; }
; __device__ __forceinline__ void attn_phase(const Params& p, LAS unsigned char* lds, int li, int tid, int G, bf16_t* __restrict__ dst, const bf16_t* __restrict__ ZGA) {
;     ...
;                 u32x4 raw[4]; float ss = 0.f;
; #pragma unroll
;                 for (int ks = 0; ks < 4; ++ks) { raw[ks] = qraw[mb][ks];
; #pragma unroll
;                     for (int e = 0; e < 4; ++e) { const float a = bf_lo(raw[ks][e]), b = bf_hi(raw[ks][e]); ss += a * a + b * b; } }
;                 ss += __shfl_xor(ss, 16); ss += __shfl_xor(ss, 32);
;                 const float rq = rsqrtf(ss * (1.f / 128.f) + EPS) * (0.08838834764831845f * LOG2E);
; #pragma unroll
;                 for (int ks = 0; ks < 4; ++ks) {
;                     const f32x4 g0 = *(const f32x4*)(qg + 32 * ks + 8 * g) * *(const f32x4*)(kg + 32 * ks + 8 * g), g1 = *(const f32x4*)(qg + 32 * ks + 8 * g + 4) * *(const f32x4*)(kg + 32 * ks + 8 * g + 4);
;                     u32x4 o;
;                     o.x = cvt_pk_bf16(bf_lo(raw[ks].x) * rq * g0[0], bf_hi(raw[ks].x) * rq * g0[1]);
;                     o.y = cvt_pk_bf16(bf_lo(raw[ks].y) * rq * g0[2], bf_hi(raw[ks].y) * rq * g0[3]);
;                     o.z = cvt_pk_bf16(bf_lo(raw[ks].z) * rq * g1[0], bf_hi(raw[ks].z) * rq * g1[1]);
;                     o.w = cvt_pk_bf16(bf_lo(raw[ks].w) * rq * g1[2], bf_hi(raw[ks].w) * rq * g1[3]);
;                     Qf[mb][ks] = __builtin_bit_cast(bf16x8, o);
;                 }
	v_add_f32_e32 v56, v56, v57
	ds_bpermute_b32 v57, v205, v56
	v_cvt_pk_bf16_f32 v111, v58, v59
	v_and_b32_e32 v76, 0xffff0000, v131
	s_cselect_b32 s1, 2, 1
	s_cmp_lg_u64 s[4:5], 0
	s_waitcnt lgkmcnt(0)
	v_add_f32_e32 v36, v56, v57
	v_fmamk_f32 v36, v36, 0x3c000000, v201
	v_mul_f32_e32 v37, 0x4b800000, v36
	v_cmp_gt_f32_e32 vcc, s87, v36
	s_addc_u32 s39, s1, 0
	s_cmp_gt_i32 s97, -1
	v_cndmask_b32_e32 v36, v36, v37, vcc
	v_rsq_f32_e32 v36, v36
	v_and_b32_e32 v37, 0xffff0000, v145
	s_cselect_b64 s[50:51], -1, 0
	s_lshl_b32 s1, s97, 5
	v_mul_f32_e32 v34, 0x45800000, v36
	v_cndmask_b32_e32 v34, v36, v34, vcc
	v_mul_f32_e32 v58, 0x3e0293ee, v34
	v_mul_f32_e32 v34, v58, v60
	v_mul_f32_e32 v34, v24, v34
	v_mul_f32_e32 v35, v58, v61
	v_mul_f32_e32 v35, v25, v35
	v_cvt_pk_bf16_f32 v114, v34, v35
	v_mul_f32_e32 v34, v58, v62
	v_mul_f32_e32 v34, v14, v34
	v_mul_f32_e32 v35, v58, v63
	v_mul_f32_e32 v35, v15, v35
	v_cvt_pk_bf16_f32 v115, v34, v35
	v_mul_f32_e32 v34, v58, v64
	v_mul_f32_e32 v34, v8, v34
	v_mul_f32_e32 v35, v58, v65
	v_mul_f32_e32 v35, v9, v35
	v_cvt_pk_bf16_f32 v116, v34, v35
	v_mul_f32_e32 v34, v58, v66
	v_mul_f32_e32 v34, v2, v34
	v_mul_f32_e32 v35, v58, v67
	v_mul_f32_e32 v35, v3, v35
	v_cvt_pk_bf16_f32 v117, v34, v35
	v_mul_f32_e32 v34, v58, v68
	v_mul_f32_e32 v34, v26, v34
	v_mul_f32_e32 v35, v58, v69
	v_mul_f32_e32 v35, v27, v35
	v_cvt_pk_bf16_f32 v118, v34, v35
	v_mul_f32_e32 v34, v58, v70
	v_mul_f32_e32 v34, v16, v34
	v_mul_f32_e32 v35, v58, v71
	v_mul_f32_e32 v35, v17, v35
	v_cvt_pk_bf16_f32 v119, v34, v35
	v_mul_f32_e32 v34, v58, v72
	v_mul_f32_e32 v34, v10, v34
	v_mul_f32_e32 v35, v58, v73
	v_mul_f32_e32 v35, v11, v35
	v_cvt_pk_bf16_f32 v120, v34, v35
	v_mul_f32_e32 v34, v58, v74
	v_mul_f32_e32 v34, v4, v34
	v_mul_f32_e32 v35, v58, v75
	v_mul_f32_e32 v35, v5, v35
	v_cvt_pk_bf16_f32 v121, v34, v35
	v_mul_f32_e32 v34, v58, v40
	v_mul_f32_e32 v34, v28, v34
	v_mul_f32_e32 v35, v58, v42
	v_mul_f32_e32 v35, v29, v35
	v_cvt_pk_bf16_f32 v122, v34, v35
	v_mul_f32_e32 v34, v58, v41
	v_mul_f32_e32 v34, v18, v34
	v_mul_f32_e32 v35, v58, v43
	v_mul_f32_e32 v35, v19, v35
	v_cvt_pk_bf16_f32 v123, v34, v35
	v_mul_f32_e32 v34, v58, v44
	v_mul_f32_e32 v34, v12, v34
	v_mul_f32_e32 v35, v58, v46
	v_mul_f32_e32 v35, v13, v35
	v_cvt_pk_bf16_f32 v124, v34, v35
	v_mul_f32_e32 v34, v58, v45
	v_mul_f32_e32 v34, v6, v34
	v_mul_f32_e32 v35, v58, v47
	v_mul_f32_e32 v35, v7, v35
	v_cvt_pk_bf16_f32 v125, v34, v35
	v_mul_f32_e32 v34, v58, v48
	v_mul_f32_e32 v34, v32, v34
	v_mul_f32_e32 v35, v58, v50
	v_mul_f32_e32 v35, v33, v35
	v_cvt_pk_bf16_f32 v126, v34, v35
	v_mul_f32_e32 v34, v58, v49
	v_mul_f32_e32 v59, v22, v34
	v_mul_f32_e32 v34, v58, v51
	v_and_b32_e32 v62, 0xffff0000, v132
	v_and_b32_e32 v64, 0xffff0000, v133
	v_mul_f32_e32 v60, v23, v34
	v_lshlrev_b32_e32 v61, 16, v132
	v_mul_f32_e32 v34, v62, v62
	v_lshlrev_b32_e32 v63, 16, v133
	v_mul_f32_e32 v35, v64, v64
	v_fmac_f32_e32 v34, v61, v61
	v_fmac_f32_e32 v35, v63, v63
	v_and_b32_e32 v66, 0xffff0000, v134
	v_add_f32_e32 v34, v34, v35
	v_lshlrev_b32_e32 v65, 16, v134
	v_mul_f32_e32 v35, v66, v66
	v_fmac_f32_e32 v35, v65, v65
	v_and_b32_e32 v68, 0xffff0000, v135
	v_add_f32_e32 v34, v35, v34
	v_lshlrev_b32_e32 v67, 16, v135
	v_mul_f32_e32 v35, v68, v68
	v_fmac_f32_e32 v35, v67, v67
	v_and_b32_e32 v70, 0xffff0000, v128
	v_add_f32_e32 v34, v35, v34
	v_lshlrev_b32_e32 v69, 16, v128
	v_mul_f32_e32 v35, v70, v70
	v_fmac_f32_e32 v35, v69, v69
	v_and_b32_e32 v72, 0xffff0000, v129
	v_add_f32_e32 v34, v35, v34
	v_lshlrev_b32_e32 v71, 16, v129
	v_mul_f32_e32 v35, v72, v72
	v_fmac_f32_e32 v35, v71, v71
	v_and_b32_e32 v74, 0xffff0000, v130
	v_add_f32_e32 v34, v35, v34
	v_lshlrev_b32_e32 v73, 16, v130
	v_mul_f32_e32 v35, v74, v74
	v_fmac_f32_e32 v35, v73, v73
	v_add_f32_e32 v34, v35, v34
	v_lshlrev_b32_e32 v75, 16, v131
	v_mul_f32_e32 v35, v76, v76
	v_fmac_f32_e32 v35, v75, v75
	v_and_b32_e32 v36, 0xffff0000, v144
	v_add_f32_e32 v42, v35, v34
	v_lshlrev_b32_e32 v35, 16, v145
	v_lshlrev_b32_e32 v34, 16, v144
	v_pk_mul_f32 v[40:41], v[36:37], v[36:37]
	v_and_b32_e32 v43, 0xffff0000, v147
	v_pk_fma_f32 v[40:41], v[34:35], v[34:35], v[40:41]
	v_and_b32_e32 v47, 0xffff0000, v141
	v_add_f32_e32 v40, v40, v42
	v_and_b32_e32 v42, 0xffff0000, v146
	v_add_f32_e32 v46, v41, v40
	v_lshlrev_b32_e32 v41, 16, v147
	v_lshlrev_b32_e32 v40, 16, v146
	v_pk_mul_f32 v[44:45], v[42:43], v[42:43]
	v_and_b32_e32 v51, 0xffff0000, v143
	v_pk_fma_f32 v[44:45], v[40:41], v[40:41], v[44:45]
	v_mul_f32_e32 v52, v58, v52
	v_add_f32_e32 v44, v44, v46
	v_and_b32_e32 v46, 0xffff0000, v140
	v_add_f32_e32 v50, v45, v44
	v_lshlrev_b32_e32 v45, 16, v141
	v_lshlrev_b32_e32 v44, 16, v140
	v_pk_mul_f32 v[48:49], v[46:47], v[46:47]
	v_mul_f32_e32 v52, v30, v52
	v_pk_fma_f32 v[48:49], v[44:45], v[44:45], v[48:49]
	v_mul_f32_e32 v54, v58, v54
	v_add_f32_e32 v48, v48, v50
	v_and_b32_e32 v50, 0xffff0000, v142
	v_add_f32_e32 v77, v49, v48
	v_lshlrev_b32_e32 v49, 16, v143
	v_lshlrev_b32_e32 v48, 16, v142
	v_pk_mul_f32 v[56:57], v[50:51], v[50:51]
	v_mul_f32_e32 v54, v31, v54
	v_pk_fma_f32 v[56:57], v[48:49], v[48:49], v[56:57]
	v_cvt_pk_bf16_f32 v128, v52, v54
	v_mul_f32_e32 v52, v58, v53
	v_add_f32_e32 v56, v56, v77
	v_add_f32_e32 v56, v57, v56
	ds_bpermute_b32 v57, v204, v56
	v_mul_f32_e32 v52, v20, v52
	s_and_b32 s41, s1, 0x7fffff80
	s_lshl_b32 s1, s97, 7
	s_and_b32 s28, s1, 0x180
	s_waitcnt lgkmcnt(0)
	v_add_f32_e32 v56, v56, v57
	ds_bpermute_b32 v57, v205, v56
	s_lshl_b32 s1, s28, 1
	s_add_u32 s52, s22, s1
	s_addc_u32 s53, s23, 0
	s_lshl_b32 s1, s41, 1
	s_waitcnt lgkmcnt(0)
; #define LAS __attribute__((address_space(3)))
; __device__ __forceinline__ unsigned cvt_pk_bf16(float lo, float hi) { unsigned r; asm("v_cvt_pk_bf16_f32 %0, %1, %2" : "=v"(r) : "v"(lo), "v"(hi)); return r; }
; __device__ __forceinline__ void attn_phase(const Params& p, LAS unsigned char* lds, int li, int tid, int G, bf16_t* __restrict__ dst, const bf16_t* __restrict__ ZGA) {
;     ...
;                 const float rq = rsqrtf(ss * (1.f / 128.f) + EPS) * (0.08838834764831845f * LOG2E);
; #pragma unroll
;                 for (int ks = 0; ks < 4; ++ks) {
;                     const f32x4 g0 = *(const f32x4*)(qg + 32 * ks + 8 * g) * *(const f32x4*)(kg + 32 * ks + 8 * g), g1 = *(const f32x4*)(qg + 32 * ks + 8 * g + 4) * *(const f32x4*)(kg + 32 * ks + 8 * g + 4);
;                     u32x4 o;
;                     o.x = cvt_pk_bf16(bf_lo(raw[ks].x) * rq * g0[0], bf_hi(raw[ks].x) * rq * g0[1]);
;                     o.y = cvt_pk_bf16(bf_lo(raw[ks].y) * rq * g0[2], bf_hi(raw[ks].y) * rq * g0[3]);
;                     o.z = cvt_pk_bf16(bf_lo(raw[ks].z) * rq * g1[0], bf_hi(raw[ks].z) * rq * g1[1]);
;                     o.w = cvt_pk_bf16(bf_lo(raw[ks].w) * rq * g1[2], bf_hi(raw[ks].w) * rq * g1[3]);
;                     Qf[mb][ks] = __builtin_bit_cast(bf16x8, o);
;                 }
;             }
;         }
;         f32x4 oacc[3][8];
;         float lrun[3];
; #pragma unroll
;         for (int mb = 0; mb < 3; ++mb) {
;             lrun[mb] = 0.f;
; #pragma unroll
;             for (int db = 0; db < 8; ++db) oacc[mb][db] = (f32x4){0.f, 0.f, 0.f, 0.f};
;         }
; #pragma unroll 1
;         for (int step = 0; step < nkb; ++step) {
;             const int kb = (step == 0) ? 1 : ((step == 1 && has0) ? 0 : 2);
;             asm volatile("s_waitcnt vmcnt(0)" ::: "memory");
;             LAS unsigned char* KS = lds + buf * 65536; LAS unsigned char* VS = KS + 32768;
;             {
;                 const int key = 16 * w + (l >> 2), part = l & 3;
	v_add_f32_e32 v53, v56, v57
	v_fmamk_f32 v53, v53, 0x3c000000, v201
	v_mul_f32_e32 v54, 0x4b800000, v53
	v_cmp_gt_f32_e32 vcc, s87, v53
	s_add_u32 s54, s24, s1
	v_and_b32_e32 v208, 15, v0
	v_cndmask_b32_e32 v53, v53, v54, vcc
	v_rsq_f32_e32 v53, v53
	v_mul_f32_e32 v54, v58, v55
	v_mul_f32_e32 v54, v21, v54
	v_cvt_pk_bf16_f32 v129, v52, v54
	v_mul_f32_e32 v52, 0x45800000, v53
	v_cndmask_b32_e32 v52, v53, v52, vcc
	v_mul_f32_e32 v52, 0x3e0293ee, v52
	v_mul_f32_e32 v53, v52, v61
	v_mul_f32_e32 v24, v24, v53
	v_mul_f32_e32 v53, v52, v62
	v_mul_f32_e32 v25, v25, v53
	v_cvt_pk_bf16_f32 v130, v24, v25
	v_mul_f32_e32 v24, v52, v63
	v_mul_f32_e32 v14, v14, v24
	v_mul_f32_e32 v24, v52, v64
	v_mul_f32_e32 v15, v15, v24
	v_cvt_pk_bf16_f32 v131, v14, v15
	v_mul_f32_e32 v14, v52, v65
	v_mul_f32_e32 v8, v8, v14
	v_mul_f32_e32 v14, v52, v66
	v_mul_f32_e32 v9, v9, v14
	v_cvt_pk_bf16_f32 v132, v8, v9
	v_mul_f32_e32 v8, v52, v67
	v_mul_f32_e32 v2, v2, v8
	v_mul_f32_e32 v8, v52, v68
	v_mul_f32_e32 v3, v3, v8
	v_cvt_pk_bf16_f32 v133, v2, v3
	v_mul_f32_e32 v2, v52, v69
	v_mul_f32_e32 v2, v26, v2
	v_mul_f32_e32 v3, v52, v70
	v_mul_f32_e32 v3, v27, v3
	v_cvt_pk_bf16_f32 v134, v2, v3
	v_mul_f32_e32 v2, v52, v71
	v_mul_f32_e32 v2, v16, v2
	v_mul_f32_e32 v3, v52, v72
	v_mul_f32_e32 v3, v17, v3
	v_cvt_pk_bf16_f32 v135, v2, v3
	v_mul_f32_e32 v2, v52, v73
	v_mul_f32_e32 v2, v10, v2
	v_mul_f32_e32 v3, v52, v74
	v_mul_f32_e32 v3, v11, v3
	v_cvt_pk_bf16_f32 v136, v2, v3
	v_mul_f32_e32 v2, v52, v75
	v_mul_f32_e32 v2, v4, v2
	v_mul_f32_e32 v3, v52, v76
	v_mul_f32_e32 v3, v5, v3
	v_cvt_pk_bf16_f32 v137, v2, v3
	v_mul_f32_e32 v2, v52, v34
	v_mul_f32_e32 v2, v28, v2
	v_mul_f32_e32 v3, v52, v36
	v_mul_f32_e32 v3, v29, v3
	v_cvt_pk_bf16_f32 v138, v2, v3
	v_mul_f32_e32 v2, v52, v35
	v_mul_f32_e32 v2, v18, v2
	v_mul_f32_e32 v3, v52, v37
	v_mul_f32_e32 v3, v19, v3
	v_cvt_pk_bf16_f32 v139, v2, v3
	v_mul_f32_e32 v2, v52, v40
	v_mul_f32_e32 v2, v12, v2
	v_mul_f32_e32 v3, v52, v42
	v_mul_f32_e32 v3, v13, v3
	v_cvt_pk_bf16_f32 v140, v2, v3
	v_mul_f32_e32 v2, v52, v41
	v_mul_f32_e32 v2, v6, v2
	v_mul_f32_e32 v3, v52, v43
	v_mul_f32_e32 v3, v7, v3
	v_cvt_pk_bf16_f32 v141, v2, v3
	v_mul_f32_e32 v2, v52, v44
	v_mul_f32_e32 v2, v32, v2
	v_mul_f32_e32 v3, v52, v46
	v_mul_f32_e32 v3, v33, v3
	v_cvt_pk_bf16_f32 v142, v2, v3
	v_mul_f32_e32 v2, v52, v45
	v_mul_f32_e32 v2, v22, v2
	v_mul_f32_e32 v3, v52, v47
	v_mul_f32_e32 v3, v23, v3
	v_cvt_pk_bf16_f32 v143, v2, v3
	v_mul_f32_e32 v2, v52, v48
	v_mul_f32_e32 v2, v30, v2
	v_mul_f32_e32 v3, v52, v50
	v_mul_f32_e32 v3, v31, v3
	v_cvt_pk_bf16_f32 v144, v2, v3
	v_mul_f32_e32 v2, v52, v49
	v_mul_f32_e32 v2, v20, v2
	v_mul_f32_e32 v3, v52, v51
	v_mul_f32_e32 v3, v21, v3
	v_cvt_pk_bf16_f32 v145, v2, v3
	v_ashrrev_i32_e32 v2, 2, v0
	v_add_lshl_u32 v171, v2, s35, 8
	v_lshlrev_b32_e32 v3, 2, v0
	v_and_b32_e32 v2, 15, v2
	v_and_b32_e32 v4, 12, v3
	v_bitop3_b32 v3, v3, v2, 12 bitop3:0x6c
	v_lshlrev_b32_e32 v177, 4, v3
	v_bitop3_b32 v3, v4, v2, 1 bitop3:0x36
	v_lshlrev_b32_e32 v178, 4, v3
	v_bitop3_b32 v3, v4, v2, 2 bitop3:0x36
	v_bitop3_b32 v2, v4, v2, 3 bitop3:0x36
	v_lshlrev_b32_e32 v180, 4, v2
	v_xor_b32_e32 v2, 1, v202
	v_cmp_lt_i32_e32 vcc, v2, v39
	s_addc_u32 s55, s25, 0
	s_lshl_b32 s1, s34, 5
	v_cndmask_b32_e32 v2, v202, v2, vcc
	v_lshlrev_b32_e32 v181, 2, v2
	v_xor_b32_e32 v2, 2, v202
	v_cmp_lt_i32_e32 vcc, v2, v39
	v_lshlrev_b32_e32 v179, 4, v3
	v_add_u32_e32 v3, 4, v38
	v_cndmask_b32_e32 v2, v202, v2, vcc
	s_and_b32 s29, s1, 0xffffff80
	s_lshl_b32 s1, s34, 7
	v_lshlrev_b32_e32 v174, 8, v208
	v_lshlrev_b32_e32 v182, 2, v2
	v_bitop3_b32 v2, v38, v0, 15 bitop3:0x78
	v_bitop3_b32 v3, v3, v0, 15 bitop3:0x78
	v_add_u32_e32 v4, 8, v38
	v_add_u32_e32 v5, 12, v38
	s_and_b32 s1, s1, 0x180
	v_lshlrev_b32_e32 v170, 2, v38
	v_ashrrev_i32_e32 v176, 5, v0
	v_bitop3_b32 v4, v4, v0, 15 bitop3:0x78
	v_bitop3_b32 v0, v5, v0, 15 bitop3:0x78
	v_lshl_add_u32 v184, v2, 4, v174
	v_lshl_add_u32 v185, v3, 4, v174
	v_mov_b32_e32 v2, v1
	v_mov_b32_e32 v3, v1
	v_cvt_pk_bf16_f32 v127, v59, v60
	s_lshl_b32 s4, s1, 1
	v_add_u32_e32 v5, s85, v170
	v_lshl_add_u32 v187, v0, 4, v174
	v_mov_b32_e32 v0, v1
	v_mov_b64_e32 v[80:81], v[2:3]
	v_mov_b64_e32 v[84:85], v[2:3]
	v_mov_b64_e32 v[88:89], v[2:3]
	v_mov_b64_e32 v[92:93], v[2:3]
	v_mov_b64_e32 v[96:97], v[2:3]
	v_mov_b64_e32 v[76:77], v[2:3]
	v_mov_b64_e32 v[72:73], v[2:3]
	v_mov_b64_e32 v[68:69], v[2:3]
	v_mov_b64_e32 v[64:65], v[2:3]
	v_mov_b64_e32 v[60:61], v[2:3]
	v_mov_b64_e32 v[56:57], v[2:3]
	v_mov_b64_e32 v[52:53], v[2:3]
	v_mov_b64_e32 v[48:49], v[2:3]
	v_mov_b64_e32 v[44:45], v[2:3]
	v_mov_b64_e32 v[40:41], v[2:3]
	v_mov_b64_e32 v[36:37], v[2:3]
	v_mov_b64_e32 v[32:33], v[2:3]
	v_mov_b64_e32 v[28:29], v[2:3]
	v_mov_b64_e32 v[24:25], v[2:3]
	v_mov_b64_e32 v[20:21], v[2:3]
	v_mov_b64_e32 v[16:17], v[2:3]
	v_mov_b64_e32 v[12:13], v[2:3]
	v_mov_b64_e32 v[8:9], v[2:3]
	s_add_u32 s56, s22, s4
	v_sub_u32_e32 v183, v5, v208
	v_lshl_add_u32 v186, v4, 4, v174
	v_mov_b64_e32 v[78:79], v[0:1]
	v_mov_b64_e32 v[82:83], v[0:1]
	v_mov_b64_e32 v[86:87], v[0:1]
	v_mov_b64_e32 v[90:91], v[0:1]
	v_mov_b64_e32 v[94:95], v[0:1]
	v_mov_b64_e32 v[74:75], v[0:1]
	v_mov_b64_e32 v[70:71], v[0:1]
	v_mov_b64_e32 v[66:67], v[0:1]
	v_mov_b64_e32 v[62:63], v[0:1]
	v_mov_b64_e32 v[58:59], v[0:1]
	v_mov_b64_e32 v[54:55], v[0:1]
	v_mov_b64_e32 v[50:51], v[0:1]
	v_mov_b64_e32 v[46:47], v[0:1]
	v_mov_b64_e32 v[42:43], v[0:1]
	v_mov_b64_e32 v[38:39], v[0:1]
	v_mov_b64_e32 v[34:35], v[0:1]
	v_mov_b64_e32 v[30:31], v[0:1]
	v_mov_b64_e32 v[26:27], v[0:1]
	v_mov_b64_e32 v[22:23], v[0:1]
	v_mov_b64_e32 v[18:19], v[0:1]
	v_mov_b64_e32 v[14:15], v[0:1]
	v_mov_b64_e32 v[10:11], v[0:1]
	v_mov_b64_e32 v[6:7], v[0:1]
	v_mov_b64_e32 v[4:5], v[2:3]
	s_mov_b32 s0, 0
	s_addc_u32 s57, s23, 0
	v_and_b32_e32 v175, 8, v172
	v_mov_b32_e32 v206, 0
	v_mov_b32_e32 v207, 0
	v_mov_b32_e32 v209, 0
	v_mov_b64_e32 v[2:3], v[0:1]
